# post phases: row-invariant g_v and short-conv weight tables copied once into LDS per wave; in-loop global weight loads replaced by ds_read_b128 with lgkmcnt waits
# baseline (speedup 1.0000x reference)
;     __device__ __forceinline__ bf16_t* bfp(size_t off) const { return (bf16_t*)(ws + off); }
;     __device__ __forceinline__ float* fp(size_t off) const { return (float*)(ws + off); }
; __device__ void phase_post(const Ctx& c, int l, bool ctx_full) {
;     const KParams pk = c.p;
;     const bf16_t* Z = c.bfp(WS_Z);
;     bf16_t* Qo = c.bfp(WS_Q); bf16_t* Ko = c.bfp(WS_K); bf16_t* Vo = c.bfp(WS_V); bf16_t* VN = c.bfp(WS_VN);
;     bf16_t* AM0 = c.bfp(WS_AM); bf16_t* AM1 = c.bfp(WS_AM + (size_t)TT * 1024 * 2);
;     const int l16 = c.lane & 15, grp = c.lane >> 4, axis = l16 >> 3, fb = (l16 & 3) * 8;
;     const bool firsth = (l16 & 4) == 0;
;     float gqo[8], gqp[8], gko[8], gkp[8];
; #pragma unroll
;     for (int i = 0; i < 8; ++i) { gqo[i] = pk->in[8][l * 128 + 8 * l16 + i]; gqp[i] = pk->in[8][l * 128 + 8 * (l16 ^ 4) + i]; gko[i] = pk->in[9][l * 128 + 8 * l16 + i]; gkp[i] = pk->in[9][l * 128 + 8 * (l16 ^ 4) + i]; }
;     const float* rope = c.fp(WS_ROPE);
;     const float* kvp = c.fp(WS_AM + (size_t)2 * TT * 1024 * 2);
;     const float* gv = pk->in[12] + l * 1024; const float* wsc = pk->in[13] + (size_t)l * 3 * 1024;
;     for (int row = c.bid * 8 + c.wave; row < TT; row += c.G * 8) {
;         const bool lat = row < TL; int b, t, slen;
;         if (lat) { b = row >> 11; t = row & 2047; slen = SEQL; } else { b = (row - TL) >> 8; t = (row - TL) & 255; slen = CTXL; }
;         const bool full = lat || ctx_full;
;         const bf16_t* zr = Z + (size_t)row * IN_DIM;
;         float cs[8], sn[8];
;         if (lat) { const float* rp = rope + ((size_t)t * 64 + axis * 32 + fb) * 2;
; #pragma unroll
;             for (int i = 0; i < 4; ++i) { const f32x4 v = *(const f32x4*)(rp + i * 4); cs[2 * i] = v[0]; sn[2 * i] = v[1]; cs[2 * i + 1] = v[2]; sn[2 * i + 1] = v[3]; } }
;         else {
; #pragma unroll
;             for (int i = 0; i < 8; ++i) { cs[i] = 1.f; sn[i] = 0.f; } }
;         const size_t kvrow = (size_t)b * SKV + (lat ? t : SEQL + t);
.LBB0_367:
	s_mov_b32 s2, 0
	s_waitcnt lgkmcnt(0)
	s_barrier
	s_mov_b32 s3, s33
	v_mbcnt_lo_u32_b32 v0, -1, s2
	v_mbcnt_hi_u32_b32 v0, -1, v0
	v_readfirstlane_b32 s2, v217
	v_lshl_or_b32 v24, s3, 6, v0
	s_mov_b64 s[4:5], s[0:1]
	v_ashrrev_i32_e32 v0, 6, v24
	v_lshl_add_u32 v48, s2, 3, v0
	s_movk_i32 s2, 0x2400
	v_cmp_gt_i32_e32 vcc, s2, v48
	s_mul_i32 s42, s38, 0x38000
	s_and_saveexec_b64 s[14:15], vcc
	s_cbranch_execz .LBB0_386
	s_load_dwordx2 s[2:3], s[4:5], 0xc0
	v_and_b32_e32 v25, 63, v24
	s_load_dwordx4 s[20:23], s[4:5], 0x40
	s_load_dwordx4 s[8:11], s[4:5], 0x60
	v_lshlrev_b32_e32 v26, 3, v25
	v_and_b32_e32 v28, 0x78, v26
	v_mov_b32_e32 v0, 0x78
	v_lshlrev_b32_e32 v29, 2, v28
	v_bitop3_b32 v0, v26, 32, v0 bitop3:0x6c
	v_lshlrev_b32_e32 v30, 2, v0
	s_waitcnt lgkmcnt(0)
	global_load_dwordx4 v[0:3], v29, s[20:21]
	global_load_dwordx4 v[4:7], v29, s[22:23]
	global_load_dwordx4 v[8:11], v29, s[20:21] offset:16
	global_load_dwordx4 v[12:15], v29, s[22:23] offset:16
	global_load_dword v43, v30, s[20:21]
	global_load_dword v47, v30, s[22:23]
	global_load_dwordx4 v[16:19], v30, s[20:21] offset:4
	global_load_dwordx3 v[40:42], v30, s[20:21] offset:20
	global_load_dwordx4 v[20:23], v30, s[22:23] offset:4
	global_load_dwordx3 v[44:46], v30, s[22:23] offset:20
	v_and_b32_e32 v32, 0x180, v26
	v_mov_b32_e32 v51, 0
	v_lshlrev_b32_e32 v50, 1, v32
	v_lshl_add_u64 v[34:35], s[2:3], 0, v[50:51]
	v_lshlrev_b32_e32 v50, 1, v28
	v_lshl_add_u64 v[34:35], v[34:35], 0, v[50:51]
	v_lshlrev_b32_e32 v50, 5, v25
	v_lshl_add_u64 v[54:55], s[8:9], 0, v[50:51]
	v_lshl_add_u64 v[58:59], s[10:11], 0, v[50:51]
	s_mov_b64 s[8:9], 0x1000
	v_lshl_add_u64 v[60:61], v[58:59], 0, s[8:9]
	s_mov_b64 s[8:9], 0x2000
	s_add_u32 s16, s2, 0x18d78000
	v_lshlrev_b32_e32 v30, 4, v25
	s_mov_b64 s[20:21], 0x2f578000
	v_lshl_add_u64 v[62:63], v[58:59], 0, s[8:9]
	s_mov_b64 s[8:9], 0x1800
	v_mov_b32_e32 v31, v51
	s_addc_u32 s17, s3, 0
	v_lshl_add_u64 v[52:53], v[34:35], 0, s[20:21]
	v_lshl_add_u64 v[64:65], v[58:59], 0, s[8:9]
	v_lshl_add_u64 v[34:35], s[2:3], 0, v[30:31]
	s_mov_b64 s[8:9], 0x30778000
	v_and_b32_e32 v27, 4, v24
	s_add_u32 s18, s2, 0x3197b600
	v_lshlrev_b32_e32 v29, 2, v25
	v_lshl_add_u64 v[68:69], v[34:35], 0, s[8:9]
	s_mov_b64 s[8:9], 0x29b78000
	v_ashrrev_i32_e32 v49, 31, v48
	v_lshlrev_b32_e32 v24, 4, v24
	v_cmp_eq_u32_e64 s[4:5], 0, v27
	s_addc_u32 s19, s3, 0
	v_and_b32_e32 v27, 48, v30
	v_xor_b32_e32 v57, 32, v29
	v_xor_b32_e32 v88, 16, v29
	v_xor_b32_e32 v89, 8, v29
	v_xor_b32_e32 v90, 4, v29
	v_xor_b32_e32 v91, 0x80, v29
	v_xor_b32_e32 v92, 64, v29
	s_lshl_b32 s22, s38, 3
	v_lshl_add_u64 v[70:71], v[34:35], 0, s[8:9]
	v_lshlrev_b64 v[34:35], 12, v[48:49]
	v_and_b32_e32 v29, 0x300, v30
	v_and_b32_e32 v30, 0xf0, v24
	v_or3_b32 v34, v34, v29, v30
	s_ashr_i32 s23, s22, 31
	v_lshl_add_u64 v[24:25], s[2:3], 0, v[34:35]
	s_mov_b64 s[8:9], 0x2d178000
	s_lshl_b64 s[24:25], s[22:23], 12
	s_movk_i32 s23, 0x7000
	v_lshl_add_u64 v[72:73], v[24:25], 0, s[8:9]
	v_mad_i64_i32 v[24:25], s[8:9], v48, s23, 0
	v_or3_b32 v24, v24, v29, v30
	s_mov_b64 s[6:7], 0x18d78000
	v_and_or_b32 v27, v26, 64, v27
	s_mov_b64 s[20:21], 0x2800
	v_lshl_add_u64 v[24:25], s[2:3], 0, v[24:25]
	v_or_b32_e32 v56, 0x200, v26
	v_lshl_add_u64 v[66:67], v[58:59], 0, s[20:21]
	v_lshl_add_u64 v[74:75], v[24:25], 0, s[6:7]
	s_mul_hi_i32 s43, s22, 0x7000
	s_mov_b64 s[26:27], 0
	s_movk_i32 s28, 0x2000
	v_lshlrev_b32_e32 v93, 2, v27
	v_mov_b32_e32 v94, 0x358637bd
	s_mov_b32 s29, 0x800000
	s_movk_i32 s30, 0x1000
	s_movk_i32 s31, 0x900
	v_lshlrev_b32_e32 v76, 1, v28
	v_lshlrev_b32_e32 v78, 1, v32
	v_lshlrev_b32_e32 v50, 1, v26
	s_movk_i32 s34, 0x23ff
	v_mov_b32_e32 v95, 0xff
	v_mov_b32_e32 v96, 0x7ff
	v_mov_b32_e32 v97, 0x100
	v_mov_b32_e32 v98, 0x800
	v_mbcnt_lo_u32_b32 v210, -1, 0
	v_mbcnt_hi_u32_b32 v210, -1, v210
	v_lshlrev_b32_e32 v210, 5, v210
	global_load_dwordx4 v[212:215], v[58:59], off
	global_load_dwordx4 v[218:221], v[58:59], off offset:16
	global_load_dwordx4 v[222:225], v[58:59], off offset:2048
	global_load_dwordx4 v[226:229], v[58:59], off offset:2064
	global_load_dwordx4 v[230:233], v[60:61], off
	global_load_dwordx4 v[234:237], v[60:61], off offset:16
	global_load_dwordx4 v[238:241], v[60:61], off offset:2048
	global_load_dwordx4 v[242:245], v[60:61], off offset:2064
	s_waitcnt vmcnt(0)
	ds_write_b128 v210, v[212:215]
	ds_write_b128 v210, v[218:221] offset:16
	ds_write_b128 v210, v[222:225] offset:2048
	ds_write_b128 v210, v[226:229] offset:2064
	ds_write_b128 v210, v[230:233] offset:4096
	ds_write_b128 v210, v[234:237] offset:4112
	ds_write_b128 v210, v[238:241] offset:6144
	ds_write_b128 v210, v[242:245] offset:6160
	s_waitcnt lgkmcnt(0)
	global_load_dwordx4 v[212:215], v[62:63], off
	global_load_dwordx4 v[218:221], v[62:63], off offset:16
	global_load_dwordx4 v[222:225], v[62:63], off offset:2048
	global_load_dwordx4 v[226:229], v[62:63], off offset:2064
	global_load_dwordx4 v[230:233], v[54:55], off
	global_load_dwordx4 v[234:237], v[54:55], off offset:16
	global_load_dwordx4 v[238:241], v[54:55], off offset:2048
	global_load_dwordx4 v[242:245], v[54:55], off offset:2064
	s_waitcnt vmcnt(0)
	ds_write_b128 v210, v[212:215] offset:8192
	ds_write_b128 v210, v[218:221] offset:8208
	ds_write_b128 v210, v[222:225] offset:10240
	ds_write_b128 v210, v[226:229] offset:10256
	ds_write_b128 v210, v[230:233] offset:12288
	ds_write_b128 v210, v[234:237] offset:12304
	ds_write_b128 v210, v[238:241] offset:14336
	ds_write_b128 v210, v[242:245] offset:14352
	s_waitcnt lgkmcnt(0)
	s_branch .LBB0_370

; __device__ __forceinline__ unsigned cvt_pk_bf16(float lo, float hi) { unsigned r; asm volatile("v_cvt_pk_bf16_f32 %0, %1, %2" : "=v"(r) : "v"(lo), "v"(hi)); return r; }
; __device__ __forceinline__ float lo_f(unsigned w) { return __uint_as_float(w << 16); }
; __device__ __forceinline__ float hi_f(unsigned w) { return __uint_as_float(w & 0xffff0000u); }
; __device__ void phase_post(const Ctx& c, int l, bool ctx_full) {
;     ...
;         for (int p = full ? 0 : 4; p < 5; ++p) {
;             const int hd = 4 * p + grp;
;             u32x4 raw;
;             if (full) raw = *(const u32x4*)(zr + hd * 128 + 8 * l16);
;             else raw = kv_share8(kvp + (size_t)(row - TL) * 1024 + grp * 128 + 8 * l16);
;             float own[8] = {lo_f(raw.x), hi_f(raw.x), lo_f(raw.y), hi_f(raw.y), lo_f(raw.z), hi_f(raw.z), lo_f(raw.w), hi_f(raw.w)};
;             float ss = 0.f;
; #pragma unroll
;             for (int i = 0; i < 8; ++i) ss += own[i] * own[i];
; #pragma unroll
;             for (int o = 8; o; o >>= 1) ss += __int_as_float(__builtin_amdgcn_ds_bpermute((c.lane ^ o) << 2, __float_as_int(ss)));
;             const float rstd = rsqrtf(ss * (1.f / 128.f) + EPS);
;             u32x4 pr;
;             pr.x = (unsigned)__builtin_amdgcn_ds_bpermute((c.lane ^ 4) << 2, (int)raw.x); pr.y = (unsigned)__builtin_amdgcn_ds_bpermute((c.lane ^ 4) << 2, (int)raw.y);
;             pr.z = (unsigned)__builtin_amdgcn_ds_bpermute((c.lane ^ 4) << 2, (int)raw.z); pr.w = (unsigned)__builtin_amdgcn_ds_bpermute((c.lane ^ 4) << 2, (int)raw.w);
;             const float par[8] = {lo_f(pr.x), hi_f(pr.x), lo_f(pr.y), hi_f(pr.y), lo_f(pr.z), hi_f(pr.z), lo_f(pr.w), hi_f(pr.w)};
;             float o8[8];
; #pragma unroll
;             for (int i = 0; i < 8; ++i) { const float on = own[i] * rstd * (p < 4 ? gqo[i] : gko[i]), pn = par[i] * rstd * (p < 4 ? gqp[i] : gkp[i]);
;                 o8[i] = firsth ? on * cs[i] - pn * sn[i] : on * cs[i] + pn * sn[i]; }
;             u32x4 w; w.x = cvt_pk_bf16(o8[0], o8[1]); w.y = cvt_pk_bf16(o8[2], o8[3]); w.z = cvt_pk_bf16(o8[4], o8[5]); w.w = cvt_pk_bf16(o8[6], o8[7]);
;             if (p < 4) *(u32x4*)(Qo + (size_t)row * DM + hd * 128 + 8 * l16) = w;
;             else *(u32x4*)(Ko + kvrow * 512 + grp * 128 + 8 * l16) = w;
.LBB0_373:
	s_nop 0
	v_mov_b64_e32 v[80:81], v[116:117]
	v_mov_b64_e32 v[82:83], v[118:119]
	v_mov_b64_e32 v[116:117], v[120:121]
	v_mov_b64_e32 v[118:119], v[122:123]
	v_mov_b64_e32 v[120:121], v[124:125]
	v_mov_b64_e32 v[122:123], v[126:127]
	v_mov_b64_e32 v[124:125], v[128:129]
	v_mov_b64_e32 v[126:127], v[130:131]
	v_lshl_add_u64 v[84:85], v[72:73], 0, s[2:3]
	s_add_u32 s2, s2, 0x400
	s_addc_u32 s3, s3, 0
	s_cmpk_eq_i32 s2, 0x1000
	v_and_b32_e32 v77, 0xffff0000, v80
	v_lshlrev_b32_e32 v49, 16, v80
	v_and_b32_e32 v86, 0xffff0000, v81
	v_lshlrev_b32_e32 v87, 16, v81
	v_mul_f32_e32 v109, v77, v77
	ds_bpermute_b32 v79, v88, v80
	ds_bpermute_b32 v106, v88, v81
	v_pk_mul_f32 v[80:81], v[86:87], v[86:87]
	v_fmac_f32_e32 v109, v49, v49
	v_and_b32_e32 v100, 0xffff0000, v82
	v_lshlrev_b32_e32 v101, 16, v82
	v_add_f32_e32 v81, v81, v109
	v_and_b32_e32 v102, 0xffff0000, v83
	v_lshlrev_b32_e32 v103, 16, v83
	ds_bpermute_b32 v107, v88, v82
	ds_bpermute_b32 v108, v88, v83
	v_pk_mul_f32 v[82:83], v[100:101], v[100:101]
	v_add_f32_e32 v80, v80, v81
	v_add_f32_e32 v80, v83, v80
	v_pk_mul_f32 v[104:105], v[102:103], v[102:103]
	v_add_f32_e32 v80, v82, v80
	v_add_f32_e32 v80, v105, v80
	v_add_f32_e32 v80, v104, v80
	ds_bpermute_b32 v82, v57, v80
	s_waitcnt lgkmcnt(4)
	v_lshlrev_b32_e32 v81, 16, v79
	s_waitcnt lgkmcnt(3)
	v_lshlrev_b32_e32 v83, 16, v106
	v_and_b32_e32 v79, 0xffff0000, v79
	v_and_b32_e32 v106, 0xffff0000, v106
	s_waitcnt lgkmcnt(0)
	v_add_f32_e32 v80, v80, v82
	ds_bpermute_b32 v82, v88, v80
	v_lshlrev_b32_e32 v109, 16, v107
	v_and_b32_e32 v107, 0xffff0000, v107
	v_lshlrev_b32_e32 v110, 16, v108
	v_and_b32_e32 v108, 0xffff0000, v108
	s_waitcnt lgkmcnt(0)
	v_add_f32_e32 v80, v80, v82
	ds_bpermute_b32 v82, v89, v80
	s_waitcnt lgkmcnt(0)
	v_add_f32_e32 v80, v80, v82
	ds_bpermute_b32 v82, v90, v80
	s_waitcnt lgkmcnt(0)
	v_add_f32_e32 v80, v80, v82
	v_fmamk_f32 v80, v80, 0x3c000000, v94
	v_mul_f32_e32 v82, 0x4b800000, v80
	v_cmp_gt_f32_e32 vcc, s29, v80
	s_nop 1
	v_cndmask_b32_e32 v80, v80, v82, vcc
	v_rsq_f32_e32 v80, v80
	s_nop 0
	v_mul_f32_e32 v82, 0x45800000, v80
	v_cndmask_b32_e32 v80, v80, v82, vcc
	v_mul_f32_e32 v81, v80, v81
	v_mul_f32_e32 v83, v80, v83
	v_mul_f32_e32 v49, v80, v49
	v_mul_f32_e32 v77, v80, v77
	v_mul_f32_e32 v79, v80, v79
	v_mul_f32_e32 v82, v80, v87
	v_mul_f32_e32 v86, v80, v86
	v_mul_f32_e32 v87, v80, v106
	v_mul_f32_e32 v101, v80, v101
	v_mul_f32_e32 v104, v80, v109
	v_mul_f32_e32 v100, v80, v100
	v_mul_f32_e32 v105, v80, v107
	v_mul_f32_e32 v103, v80, v103
	v_mul_f32_e32 v106, v80, v110
	v_mul_f32_e32 v102, v80, v102
	v_mul_f32_e32 v80, v80, v108
	v_mul_f32_e32 v81, v43, v81
	v_mul_f32_e32 v83, v17, v83
	v_mul_f32_e32 v79, v16, v79
	v_mul_f32_e32 v87, v18, v87
	v_mul_f32_e32 v104, v19, v104
	v_mul_f32_e32 v105, v40, v105
	v_mul_f32_e32 v106, v41, v106
	v_mul_f32_e32 v80, v42, v80
	v_mul_f32_e32 v81, v25, v81
	v_mul_f32_e32 v83, v29, v83
	v_mul_f32_e32 v49, v0, v49
	v_mul_f32_e32 v82, v2, v82
	v_mul_f32_e32 v79, v27, v79
	v_mul_f32_e32 v87, v31, v87
	v_mul_f32_e32 v104, v33, v104
	v_mul_f32_e32 v105, v35, v105
	v_mul_f32_e32 v106, v37, v106
	v_mul_f32_e32 v80, v39, v80
	v_cndmask_b32_e64 v81, v81, -v81, s[4:5]
	v_cndmask_b32_e64 v83, v83, -v83, s[4:5]
	v_mul_f32_e32 v77, v1, v77
	v_mul_f32_e32 v86, v3, v86
	v_mul_f32_e32 v101, v8, v101
	v_mul_f32_e32 v100, v9, v100
	v_mul_f32_e32 v103, v10, v103
	v_mul_f32_e32 v102, v11, v102
	v_cndmask_b32_e64 v79, v79, -v79, s[4:5]
	v_cndmask_b32_e64 v87, v87, -v87, s[4:5]
	v_cndmask_b32_e64 v104, v104, -v104, s[4:5]
	v_cndmask_b32_e64 v105, v105, -v105, s[4:5]
	v_cndmask_b32_e64 v106, v106, -v106, s[4:5]
	v_cndmask_b32_e64 v107, v80, -v80, s[4:5]
	v_fmac_f32_e32 v81, v24, v49
	v_fmac_f32_e32 v83, v28, v82
	v_fmac_f32_e32 v79, v26, v77
	v_fmac_f32_e32 v87, v30, v86
	v_fmac_f32_e32 v104, v32, v101
	v_fmac_f32_e32 v105, v34, v100
	v_fmac_f32_e32 v106, v36, v103
	v_fmac_f32_e32 v107, v38, v102
	v_cvt_pk_bf16_f32 v80, v81, v79
	v_cvt_pk_bf16_f32 v81, v83, v87
	v_cvt_pk_bf16_f32 v82, v104, v105
	v_cvt_pk_bf16_f32 v83, v106, v107
	global_store_dwordx4 v[84:85], v[80:83], off
	s_cbranch_scc0 .LBB0_373
	s_nop 0
	v_mov_b64_e32 v[80:81], s[16:17]
	v_mad_i64_i32 v[80:81], s[2:3], v48, s23, v[80:81]
	v_mov_b32_e32 v77, v51
	v_lshl_add_u64 v[82:83], v[80:81], 0, v[76:77]
	v_mov_b32_e32 v79, v51
	v_lshl_add_u64 v[82:83], v[82:83], 0, v[78:79]
	v_add_co_u32_e32 v82, vcc, s30, v82
	v_add_u32_e32 v49, 0xffffe000, v48
	s_nop 0
	v_addc_co_u32_e32 v83, vcc, 0, v83, vcc
	v_mov_b64_e32 v[84:85], v[132:133]
	v_mov_b64_e32 v[86:87], v[134:135]
	v_ashrrev_i32_e32 v77, 11, v48
	v_lshrrev_b32_e32 v49, 8, v49
	v_or_b32_e32 v79, 0x800, v99
	v_cndmask_b32_e64 v49, v49, v77, s[6:7]
	v_mov_b32_e32 v101, v51
	v_and_b32_e32 v113, 0xffff0000, v84
	v_lshlrev_b32_e32 v112, 16, v84
	v_and_b32_e32 v102, 0xffff0000, v85
	v_lshlrev_b32_e32 v103, 16, v85
	v_mul_f32_e32 v100, v113, v113
	v_pk_mul_f32 v[82:83], v[102:103], v[102:103]
	v_fmac_f32_e32 v100, v112, v112
	v_and_b32_e32 v104, 0xffff0000, v86
	v_lshlrev_b32_e32 v105, 16, v86
	v_add_f32_e32 v83, v83, v100
	v_pk_mul_f32 v[108:109], v[104:105], v[104:105]
	v_add_f32_e32 v82, v82, v83
	v_and_b32_e32 v106, 0xffff0000, v87
	v_lshlrev_b32_e32 v107, 16, v87
	v_add_f32_e32 v82, v109, v82
	v_pk_mul_f32 v[110:111], v[106:107], v[106:107]
	v_add_f32_e32 v82, v108, v82
	v_add_f32_e32 v82, v111, v82
	v_add_f32_e32 v108, v110, v82
	ds_bpermute_b32 v109, v57, v108
	v_cndmask_b32_e64 v100, v79, v99, s[6:7]
	v_mad_i64_i32 v[100:101], s[2:3], v49, s31, v[100:101]
	ds_bpermute_b32 v49, v88, v84
	s_waitcnt lgkmcnt(1)
; __device__ __forceinline__ float lo_f(unsigned w) { return __uint_as_float(w << 16); }
; __device__ void phase_post(const Ctx& c, int l, bool ctx_full) {
;     ...
;         for (int p = full ? 0 : 4; p < 5; ++p) {
;             const int hd = 4 * p + grp;
;             u32x4 raw;
;             if (full) raw = *(const u32x4*)(zr + hd * 128 + 8 * l16);
;             else raw = kv_share8(kvp + (size_t)(row - TL) * 1024 + grp * 128 + 8 * l16);
;             float own[8] = {lo_f(raw.x), hi_f(raw.x), lo_f(raw.y), hi_f(raw.y), lo_f(raw.z), hi_f(raw.z), lo_f(raw.w), hi_f(raw.w)};
;             float ss = 0.f;
; #pragma unroll
;             for (int i = 0; i < 8; ++i) ss += own[i] * own[i];
; #pragma unroll
;             for (int o = 8; o; o >>= 1) ss += __int_as_float(__builtin_amdgcn_ds_bpermute((c.lane ^ o) << 2, __float_as_int(ss)));
;             const float rstd = rsqrtf(ss * (1.f / 128.f) + EPS);
;             u32x4 pr;
;             pr.x = (unsigned)__builtin_amdgcn_ds_bpermute((c.lane ^ 4) << 2, (int)raw.x); pr.y = (unsigned)__builtin_amdgcn_ds_bpermute((c.lane ^ 4) << 2, (int)raw.y);
;             pr.z = (unsigned)__builtin_amdgcn_ds_bpermute((c.lane ^ 4) << 2, (int)raw.z); pr.w = (unsigned)__builtin_amdgcn_ds_bpermute((c.lane ^ 4) << 2, (int)raw.w);
;             const float par[8] = {lo_f(pr.x), hi_f(pr.x), lo_f(pr.y), hi_f(pr.y), lo_f(pr.z), hi_f(pr.z), lo_f(pr.w), hi_f(pr.w)};
;             float o8[8];
; #pragma unroll
;             for (int i = 0; i < 8; ++i) { const float on = own[i] * rstd * (p < 4 ? gqo[i] : gko[i]), pn = par[i] * rstd * (p < 4 ? gqp[i] : gkp[i]);
;                 o8[i] = firsth ? on * cs[i] - pn * sn[i] : on * cs[i] + pn * sn[i]; }
;             u32x4 w; w.x = cvt_pk_bf16(o8[0], o8[1]); w.y = cvt_pk_bf16(o8[2], o8[3]); w.z = cvt_pk_bf16(o8[4], o8[5]); w.w = cvt_pk_bf16(o8[6], o8[7]);
;             if (p < 4) *(u32x4*)(Qo + (size_t)row * DM + hd * 128 + 8 * l16) = w;
;             else *(u32x4*)(Ko + kvrow * 512 + grp * 128 + 8 * l16) = w;
;         }
;         if (!full) *(u32x4*)(Vo + kvrow * 512 + c.lane * 8) = kv_share8(kvp + (size_t)(row - TL) * 1024 + 512 + c.lane * 8);
;         if (full) {
;             float fv[16]; float ss = 0.f;
; #pragma unroll
;             for (int i = 0; i < 2; ++i) { const int cc = i * 512 + c.lane * 8;
;                 const u32x4 zv = *(const u32x4*)(zr + OFF_GV + cc);
	v_add_f32_e32 v77, v108, v109
	ds_bpermute_b32 v79, v88, v77
	ds_bpermute_b32 v84, v88, v85
	ds_bpermute_b32 v85, v88, v86
	ds_bpermute_b32 v86, v88, v87
	s_waitcnt lgkmcnt(4)
	v_lshlrev_b32_e32 v87, 16, v49
	s_waitcnt lgkmcnt(3)
	v_add_f32_e32 v77, v77, v79
	ds_bpermute_b32 v79, v89, v77
	v_and_b32_e32 v49, 0xffff0000, v49
	s_waitcnt lgkmcnt(2)
	v_lshlrev_b32_e32 v109, 16, v85
	v_lshlrev_b32_e32 v108, 16, v84
	v_and_b32_e32 v84, 0xffff0000, v84
	s_waitcnt lgkmcnt(0)
	v_add_f32_e32 v77, v77, v79
	ds_bpermute_b32 v79, v90, v77
	v_lshl_add_u64 v[82:83], v[80:81], 0, v[50:51]
	v_lshlrev_b64 v[100:101], 10, v[100:101]
	v_lshl_add_u64 v[100:101], v[52:53], 0, v[100:101]
	s_waitcnt lgkmcnt(0)
	v_add_f32_e32 v77, v77, v79
	v_fmamk_f32 v77, v77, 0x3c000000, v94
	v_mul_f32_e32 v79, 0x4b800000, v77
	v_cmp_gt_f32_e32 vcc, s29, v77
	s_nop 1
	v_cndmask_b32_e32 v77, v77, v79, vcc
	v_rsq_f32_e32 v77, v77
	v_and_b32_e32 v79, 0xffff0000, v85
	v_lshlrev_b32_e32 v85, 16, v86
	v_and_b32_e32 v86, 0xffff0000, v86
	v_mul_f32_e32 v110, 0x45800000, v77
	v_cndmask_b32_e32 v77, v77, v110, vcc
	v_mul_f32_e32 v87, v77, v87
	v_mul_f32_e32 v49, v77, v49
	v_mul_f32_e32 v109, v77, v109
	v_mul_f32_e32 v110, v77, v112
	v_mul_f32_e32 v111, v77, v113
	v_mul_f32_e32 v103, v77, v103
	v_mul_f32_e32 v108, v77, v108
	v_mul_f32_e32 v102, v77, v102
	v_mul_f32_e32 v84, v77, v84
	v_mul_f32_e32 v105, v77, v105
	v_mul_f32_e32 v104, v77, v104
	v_mul_f32_e32 v79, v77, v79
	v_mul_f32_e32 v107, v77, v107
	v_mul_f32_e32 v85, v77, v85
	v_mul_f32_e32 v106, v77, v106
	v_mul_f32_e32 v77, v77, v86
	v_mul_f32_e32 v87, v47, v87
	v_mul_f32_e32 v49, v20, v49
	v_mul_f32_e32 v109, v23, v109
	v_mul_f32_e32 v108, v21, v108
	v_mul_f32_e32 v84, v22, v84
	v_mul_f32_e32 v79, v44, v79
	v_mul_f32_e32 v85, v45, v85
	v_mul_f32_e32 v77, v46, v77
	v_mul_f32_e32 v25, v25, v87
	v_mul_f32_e32 v27, v27, v49
	v_mul_f32_e32 v33, v33, v109
	v_mul_f32_e32 v86, v4, v110
	v_mul_f32_e32 v110, v5, v111
	v_mul_f32_e32 v105, v12, v105
	v_mul_f32_e32 v29, v29, v108
	v_mul_f32_e32 v31, v31, v84
	v_mul_f32_e32 v35, v35, v79
	v_mul_f32_e32 v37, v37, v85
	v_mul_f32_e32 v39, v39, v77
	v_cndmask_b32_e64 v25, v25, -v25, s[4:5]
	v_cndmask_b32_e64 v27, v27, -v27, s[4:5]
	v_cndmask_b32_e64 v33, v33, -v33, s[4:5]
	v_mul_f32_e32 v103, v6, v103
	v_mul_f32_e32 v102, v7, v102
	v_mul_f32_e32 v104, v13, v104
	v_mul_f32_e32 v107, v14, v107
	v_mul_f32_e32 v106, v15, v106
	v_cndmask_b32_e64 v29, v29, -v29, s[4:5]
	v_cndmask_b32_e64 v31, v31, -v31, s[4:5]
	v_cndmask_b32_e64 v35, v35, -v35, s[4:5]
	v_cndmask_b32_e64 v37, v37, -v37, s[4:5]
	v_cndmask_b32_e64 v39, v39, -v39, s[4:5]
	v_fmac_f32_e32 v25, v24, v86
	v_fmac_f32_e32 v27, v26, v110
	v_fmac_f32_e32 v33, v32, v105
	v_add_co_u32_e32 v32, vcc, s28, v82
	v_fmac_f32_e32 v29, v28, v103
	v_fmac_f32_e32 v31, v30, v102
	v_fmac_f32_e32 v35, v34, v104
	v_fmac_f32_e32 v37, v36, v107
	v_fmac_f32_e32 v39, v38, v106
	v_cvt_pk_bf16_f32 v24, v25, v27
	v_cvt_pk_bf16_f32 v25, v29, v31
	v_cvt_pk_bf16_f32 v26, v33, v35
	v_cvt_pk_bf16_f32 v27, v37, v39
	global_store_dwordx4 v[100:101], v[24:27], off
	v_addc_co_u32_e32 v33, vcc, 0, v83, vcc
	v_mov_b64_e32 v[28:29], v[136:137]
	v_mov_b64_e32 v[30:31], v[138:139]
	v_mov_b64_e32 v[24:25], v[140:141]
	v_mov_b64_e32 v[26:27], v[142:143]
	v_lshlrev_b32_e32 v32, 16, v28
	v_and_b32_e32 v28, 0xffff0000, v28
	v_mul_f32_e32 v35, 0x3d372713, v32
	v_lshlrev_b32_e32 v33, 16, v29
	v_mul_f32_e32 v37, 0x3d372713, v28
	v_mul_f32_e32 v35, v35, v32
	v_mul_f32_e32 v36, 0.5, v32
	v_mul_f32_e32 v39, 0x3d372713, v33
	v_mul_f32_e32 v37, v37, v28
	v_fma_f32 v32, v35, v32, v32
	v_mul_f32_e32 v38, 0.5, v28
	v_mul_f32_e32 v39, v39, v33
	v_fma_f32 v28, v37, v28, v28
	v_mul_f32_e32 v32, 0x3f4c422a, v32
	v_mul_f32_e32 v49, 0.5, v33
	v_fma_f32 v33, v39, v33, v33
	v_mul_f32_e32 v28, 0x3f4c422a, v28
	v_add_f32_e32 v32, v32, v32
	v_mul_f32_e32 v33, 0x3f4c422a, v33
	v_add_f32_e32 v28, v28, v28
	v_mul_f32_e32 v32, 0x3fb8aa3b, v32
	v_add_f32_e32 v33, v33, v33
	v_mul_f32_e32 v28, 0x3fb8aa3b, v28
	v_exp_f32_e32 v32, v32
	v_mul_f32_e32 v33, 0x3fb8aa3b, v33
	v_exp_f32_e32 v28, v28
	v_exp_f32_e32 v33, v33
	v_lshlrev_b32_e32 v34, 16, v30
	v_mul_f32_e32 v79, 0x3d372713, v34
	v_add_f32_e32 v32, 1.0, v32
	v_and_b32_e32 v29, 0xffff0000, v29
	v_mul_f32_e32 v79, v79, v34
	v_add_f32_e32 v28, 1.0, v28
	v_div_scale_f32 v39, s[2:3], v32, v32, 2.0
	v_mul_f32_e32 v77, 0x3d372713, v29
	v_fma_f32 v37, v79, v34, v34
	v_add_f32_e32 v33, 1.0, v33
	v_div_scale_f32 v79, s[2:3], v28, v28, 2.0
	v_rcp_f32_e32 v101, v39
	v_mul_f32_e32 v77, v77, v29
	v_div_scale_f32 v85, s[8:9], v33, v33, 2.0
	v_rcp_f32_e32 v102, v79
	v_fma_f32 v35, v77, v29, v29
	v_rcp_f32_e32 v103, v85
	v_mul_f32_e32 v35, 0x3f4c422a, v35
	v_add_f32_e32 v35, v35, v35
	v_fma_f32 v105, -v39, v101, 1.0
	v_mul_f32_e32 v35, 0x3fb8aa3b, v35
	v_div_scale_f32 v77, vcc, 2.0, v32, 2.0
	v_fma_f32 v106, -v79, v102, 1.0
	v_fmac_f32_e32 v101, v105, v101
	v_exp_f32_e32 v35, v35
	v_div_scale_f32 v84, s[2:3], 2.0, v28, 2.0
	v_fma_f32 v107, -v85, v103, 1.0
	v_fmac_f32_e32 v102, v106, v102
	v_mul_f32_e32 v105, v77, v101
	v_div_scale_f32 v86, s[8:9], 2.0, v33, 2.0
	v_fmac_f32_e32 v103, v107, v103
	v_mul_f32_e32 v106, v84, v102
	v_fma_f32 v109, -v39, v105, v77
	v_mul_f32_e32 v107, v86, v103
	v_fma_f32 v110, -v79, v106, v84
	v_fmac_f32_e32 v105, v109, v101
	v_fma_f32 v111, -v85, v107, v86
	v_fmac_f32_e32 v106, v110, v102
	v_fma_f32 v39, -v39, v105, v77
	v_add_f32_e32 v35, 1.0, v35
	v_fmac_f32_e32 v107, v111, v103
	v_fma_f32 v77, -v79, v106, v84
	v_div_fmas_f32 v39, v39, v101, v105
	s_mov_b64 vcc, s[2:3]
	v_div_scale_f32 v87, s[10:11], v35, v35, 2.0
	v_fma_f32 v79, -v85, v107, v86
; __device__ __forceinline__ float lo_f(unsigned w) { return __uint_as_float(w << 16); }
; __device__ __forceinline__ float hi_f(unsigned w) { return __uint_as_float(w & 0xffff0000u); }
; __device__ void phase_post(const Ctx& c, int l, bool ctx_full) {
;     ...
;         if (full) {
;             float fv[16]; float ss = 0.f;
; #pragma unroll
;             for (int i = 0; i < 2; ++i) { const int cc = i * 512 + c.lane * 8;
;                 const u32x4 zv = *(const u32x4*)(zr + OFF_GV + cc);
;                 fv[i * 8 + 0] = gelu_tanh(lo_f(zv.x)); fv[i * 8 + 1] = gelu_tanh(hi_f(zv.x)); fv[i * 8 + 2] = gelu_tanh(lo_f(zv.y)); fv[i * 8 + 3] = gelu_tanh(hi_f(zv.y));
;                 fv[i * 8 + 4] = gelu_tanh(lo_f(zv.z)); fv[i * 8 + 5] = gelu_tanh(hi_f(zv.z)); fv[i * 8 + 6] = gelu_tanh(lo_f(zv.w)); fv[i * 8 + 7] = gelu_tanh(hi_f(zv.w));
; #pragma unroll
;                 for (int j = 0; j < 8; ++j) ss += fv[i * 8 + j] * fv[i * 8 + j]; }
	v_div_fixup_f32 v32, v39, v32, 2.0
	v_div_fmas_f32 v39, v77, v102, v106
	s_mov_b64 vcc, s[8:9]
	v_rcp_f32_e32 v104, v87
	v_sub_f32_e32 v32, 1.0, v32
	v_div_fixup_f32 v28, v39, v28, 2.0
	v_div_fmas_f32 v39, v79, v103, v107
	v_add_f32_e32 v32, 1.0, v32
	v_sub_f32_e32 v28, 1.0, v28
	v_div_fixup_f32 v33, v39, v33, 2.0
	v_mul_f32_e32 v37, 0x3f4c422a, v37
	v_mul_f32_e32 v77, v36, v32
	v_add_f32_e32 v28, 1.0, v28
	v_sub_f32_e32 v32, 1.0, v33
	v_add_f32_e32 v37, v37, v37
	v_mul_f32_e32 v79, v38, v28
	v_add_f32_e32 v28, 1.0, v32
	v_fma_f32 v108, -v87, v104, 1.0
	v_mul_f32_e32 v85, v49, v28
	v_mul_f32_e32 v28, 0x3fb8aa3b, v37
	v_div_scale_f32 v100, s[10:11], 2.0, v35, 2.0
	v_fmac_f32_e32 v104, v108, v104
	v_exp_f32_e32 v28, v28
	v_mul_f32_e32 v108, v100, v104
	v_fma_f32 v112, -v87, v108, v100
	v_fmac_f32_e32 v108, v112, v104
	v_fma_f32 v84, -v87, v108, v100
	s_mov_b64 vcc, s[10:11]
	v_add_f32_e32 v28, 1.0, v28
	v_div_fmas_f32 v32, v84, v104, v108
	v_div_scale_f32 v33, s[2:3], v28, v28, 2.0
	v_div_fixup_f32 v32, v32, v35, 2.0
	v_rcp_f32_e32 v35, v33
	v_sub_f32_e32 v32, 1.0, v32
	v_mul_f32_e32 v29, 0.5, v29
	v_add_f32_e32 v32, 1.0, v32
	v_mul_f32_e32 v84, v29, v32
	v_fma_f32 v29, -v33, v35, 1.0
	v_fmac_f32_e32 v35, v29, v35
	v_div_scale_f32 v29, vcc, 2.0, v28, 2.0
	v_mul_f32_e32 v32, v29, v35
	v_fma_f32 v36, -v33, v32, v29
	v_fmac_f32_e32 v32, v36, v35
	v_and_b32_e32 v30, 0xffff0000, v30
	v_fma_f32 v29, -v33, v32, v29
	v_mul_f32_e32 v33, 0x3d372713, v30
	v_mul_f32_e32 v33, v33, v30
	v_fma_f32 v33, v33, v30, v30
	v_mul_f32_e32 v33, 0x3f4c422a, v33
	v_add_f32_e32 v33, v33, v33
	v_mul_f32_e32 v33, 0x3fb8aa3b, v33
	v_exp_f32_e32 v33, v33
	v_div_fmas_f32 v29, v29, v35, v32
	v_div_fixup_f32 v28, v29, v28, 2.0
	v_sub_f32_e32 v28, 1.0, v28
	v_add_f32_e32 v29, 1.0, v33
	v_div_scale_f32 v32, s[2:3], v29, v29, 2.0
	v_rcp_f32_e32 v33, v32
	v_mul_f32_e32 v34, 0.5, v34
	v_add_f32_e32 v28, 1.0, v28
	v_mul_f32_e32 v86, v34, v28
	v_fma_f32 v28, -v32, v33, 1.0
	v_fmac_f32_e32 v33, v28, v33
	v_div_scale_f32 v28, vcc, 2.0, v29, 2.0
	v_mul_f32_e32 v34, v28, v33
	v_fma_f32 v35, -v32, v34, v28
	v_fmac_f32_e32 v34, v35, v33
	v_fma_f32 v28, -v32, v34, v28
	v_lshlrev_b32_e32 v32, 16, v31
	v_mul_f32_e32 v35, 0x3d372713, v32
	v_mul_f32_e32 v35, v35, v32
	v_fma_f32 v35, v35, v32, v32
	v_mul_f32_e32 v35, 0x3f4c422a, v35
	v_add_f32_e32 v35, v35, v35
	v_mul_f32_e32 v35, 0x3fb8aa3b, v35
	v_exp_f32_e32 v35, v35
	v_div_fmas_f32 v28, v28, v33, v34
	v_div_fixup_f32 v28, v28, v29, 2.0
	v_sub_f32_e32 v28, 1.0, v28
	v_add_f32_e32 v29, 1.0, v35
	v_div_scale_f32 v33, s[2:3], v29, v29, 2.0
	v_rcp_f32_e32 v34, v33
	v_mul_f32_e32 v30, 0.5, v30
	v_add_f32_e32 v28, 1.0, v28
	v_mul_f32_e32 v87, v30, v28
	v_fma_f32 v28, -v33, v34, 1.0
	v_fmac_f32_e32 v34, v28, v34
	v_div_scale_f32 v28, vcc, 2.0, v29, 2.0
	v_mul_f32_e32 v30, v28, v34
	v_fma_f32 v35, -v33, v30, v28
	v_fmac_f32_e32 v30, v35, v34
	v_and_b32_e32 v31, 0xffff0000, v31
	v_fma_f32 v28, -v33, v30, v28
	v_mul_f32_e32 v33, 0x3d372713, v31
	v_mul_f32_e32 v33, v33, v31
	v_fma_f32 v33, v33, v31, v31
	v_mul_f32_e32 v33, 0x3f4c422a, v33
	v_add_f32_e32 v33, v33, v33
	v_mul_f32_e32 v33, 0x3fb8aa3b, v33
	v_exp_f32_e32 v33, v33
	v_div_fmas_f32 v28, v28, v34, v30
	v_div_fixup_f32 v28, v28, v29, 2.0
	v_sub_f32_e32 v28, 1.0, v28
	v_add_f32_e32 v29, 1.0, v33
	v_div_scale_f32 v30, s[2:3], v29, v29, 2.0
	v_rcp_f32_e32 v33, v30
	v_mul_f32_e32 v32, 0.5, v32
	v_add_f32_e32 v28, 1.0, v28
	v_mul_f32_e32 v100, v32, v28
	v_fma_f32 v28, -v30, v33, 1.0
	v_fmac_f32_e32 v33, v28, v33
	v_div_scale_f32 v28, vcc, 2.0, v29, 2.0
	v_mul_f32_e32 v32, v28, v33
	v_fma_f32 v34, -v30, v32, v28
	v_fmac_f32_e32 v32, v34, v33
	v_fma_f32 v28, -v30, v32, v28
	v_div_fmas_f32 v28, v28, v33, v32
	v_div_fixup_f32 v28, v28, v29, 2.0
	v_sub_f32_e32 v28, 1.0, v28
	v_mul_f32_e32 v29, 0.5, v31
	v_add_f32_e32 v28, 1.0, v28
	v_mul_f32_e32 v101, v29, v28
	v_lshlrev_b32_e32 v28, 16, v24
	v_mul_f32_e32 v29, 0x3d372713, v28
	v_mul_f32_e32 v29, v29, v28
	v_fma_f32 v29, v29, v28, v28
	v_mul_f32_e32 v29, 0x3f4c422a, v29
	v_add_f32_e32 v29, v29, v29
	v_mul_f32_e32 v29, 0x3fb8aa3b, v29
	v_exp_f32_e32 v29, v29
	v_and_b32_e32 v24, 0xffff0000, v24
	v_mul_f32_e32 v28, 0.5, v28
	v_mul_f32_e32 v30, v79, v79
	v_add_f32_e32 v29, 1.0, v29
	v_div_scale_f32 v31, s[2:3], v29, v29, 2.0
	v_rcp_f32_e32 v32, v31
	v_fmac_f32_e32 v30, v77, v77
	v_fmac_f32_e32 v30, v85, v85
	v_fmac_f32_e32 v30, v84, v84
	v_fma_f32 v33, -v31, v32, 1.0
	v_fmac_f32_e32 v32, v33, v32
	v_div_scale_f32 v33, vcc, 2.0, v29, 2.0
	v_mul_f32_e32 v34, v33, v32
	v_fma_f32 v35, -v31, v34, v33
	v_fmac_f32_e32 v34, v35, v32
	v_fma_f32 v31, -v31, v34, v33
	v_mul_f32_e32 v33, 0x3d372713, v24
	v_mul_f32_e32 v33, v33, v24
	v_fma_f32 v33, v33, v24, v24
	v_mul_f32_e32 v33, 0x3f4c422a, v33
	v_add_f32_e32 v33, v33, v33
	v_mul_f32_e32 v33, 0x3fb8aa3b, v33
	v_exp_f32_e32 v33, v33
	v_div_fmas_f32 v31, v31, v32, v34
	v_div_fixup_f32 v29, v31, v29, 2.0
	v_sub_f32_e32 v29, 1.0, v29
	v_add_f32_e32 v31, 1.0, v33
	v_div_scale_f32 v32, s[2:3], v31, v31, 2.0
	v_rcp_f32_e32 v33, v32
	v_add_f32_e32 v29, 1.0, v29
	v_mul_f32_e32 v102, v28, v29
	v_mul_f32_e32 v24, 0.5, v24
	v_fma_f32 v28, -v32, v33, 1.0
	v_fmac_f32_e32 v33, v28, v33
	v_div_scale_f32 v28, vcc, 2.0, v31, 2.0
	v_mul_f32_e32 v29, v28, v33
	v_fma_f32 v34, -v32, v29, v28
	v_fmac_f32_e32 v29, v34, v33
	v_fma_f32 v28, -v32, v29, v28
	v_lshlrev_b32_e32 v32, 16, v25
	v_mul_f32_e32 v34, 0x3d372713, v32
	v_mul_f32_e32 v34, v34, v32
	v_fma_f32 v34, v34, v32, v32
	v_mul_f32_e32 v34, 0x3f4c422a, v34
	v_add_f32_e32 v34, v34, v34
	v_mul_f32_e32 v34, 0x3fb8aa3b, v34
	v_exp_f32_e32 v34, v34
	v_div_fmas_f32 v28, v28, v33, v29
; __device__ __forceinline__ float lo_f(unsigned w) { return __uint_as_float(w << 16); }
; __device__ __forceinline__ float hi_f(unsigned w) { return __uint_as_float(w & 0xffff0000u); }
; __device__ void phase_post(const Ctx& c, int l, bool ctx_full) {
;     ...
;                 fv[i * 8 + 0] = gelu_tanh(lo_f(zv.x)); fv[i * 8 + 1] = gelu_tanh(hi_f(zv.x)); fv[i * 8 + 2] = gelu_tanh(lo_f(zv.y)); fv[i * 8 + 3] = gelu_tanh(hi_f(zv.y));
;                 fv[i * 8 + 4] = gelu_tanh(lo_f(zv.z)); fv[i * 8 + 5] = gelu_tanh(hi_f(zv.z)); fv[i * 8 + 6] = gelu_tanh(lo_f(zv.w)); fv[i * 8 + 7] = gelu_tanh(hi_f(zv.w));
; #pragma unroll
;                 for (int j = 0; j < 8; ++j) ss += fv[i * 8 + j] * fv[i * 8 + j]; }
;             ss = wave_sum(ss, c.lane); const float rstd = rsqrtf(ss * (1.f / 1024.f) + EPS);
; #pragma unroll
;             for (int i = 0; i < 2; ++i) { const int cc = i * 512 + c.lane * 8;
;                 const f32x4 g0 = *(const f32x4*)(gv + cc), g1 = *(const f32x4*)(gv + cc + 4);
	v_div_fixup_f32 v28, v28, v31, 2.0
	v_sub_f32_e32 v28, 1.0, v28
	v_add_f32_e32 v29, 1.0, v34
	v_div_scale_f32 v31, s[2:3], v29, v29, 2.0
	v_rcp_f32_e32 v33, v31
	v_add_f32_e32 v28, 1.0, v28
	v_mul_f32_e32 v103, v24, v28
	v_and_b32_e32 v25, 0xffff0000, v25
	v_fma_f32 v24, -v31, v33, 1.0
	v_fmac_f32_e32 v33, v24, v33
	v_div_scale_f32 v24, vcc, 2.0, v29, 2.0
	v_mul_f32_e32 v28, v24, v33
	v_fma_f32 v34, -v31, v28, v24
	v_fmac_f32_e32 v28, v34, v33
	v_fma_f32 v24, -v31, v28, v24
	v_mul_f32_e32 v31, 0x3d372713, v25
	v_mul_f32_e32 v31, v31, v25
	v_fma_f32 v31, v31, v25, v25
	v_mul_f32_e32 v31, 0x3f4c422a, v31
	v_add_f32_e32 v31, v31, v31
	v_mul_f32_e32 v31, 0x3fb8aa3b, v31
	v_exp_f32_e32 v31, v31
	v_div_fmas_f32 v24, v24, v33, v28
	v_div_fixup_f32 v24, v24, v29, 2.0
	v_sub_f32_e32 v24, 1.0, v24
	v_add_f32_e32 v28, 1.0, v31
	v_div_scale_f32 v29, s[2:3], v28, v28, 2.0
	v_rcp_f32_e32 v31, v29
	v_mul_f32_e32 v32, 0.5, v32
	v_add_f32_e32 v24, 1.0, v24
	v_mul_f32_e32 v104, v32, v24
	v_fma_f32 v24, -v29, v31, 1.0
	v_fmac_f32_e32 v31, v24, v31
	v_div_scale_f32 v24, vcc, 2.0, v28, 2.0
	v_mul_f32_e32 v32, v24, v31
	v_fma_f32 v33, -v29, v32, v24
	v_fmac_f32_e32 v32, v33, v31
	v_fma_f32 v24, -v29, v32, v24
	v_div_fmas_f32 v24, v24, v31, v32
	v_div_fixup_f32 v24, v24, v28, 2.0
	v_mul_f32_e32 v32, 0.5, v25
	v_lshlrev_b32_e32 v25, 16, v26
	v_sub_f32_e32 v31, 1.0, v24
	v_and_b32_e32 v24, 0xffff0000, v26
	v_mul_f32_e32 v26, 0x3d372713, v25
	v_mul_f32_e32 v26, v26, v25
	v_mov_b32_e32 v28, v25
	v_fmac_f32_e32 v28, v26, v28
	v_mul_f32_e32 v26, 0x3f4c422a, v28
	v_add_f32_e32 v26, v26, v26
	v_mul_f32_e32 v26, 0x3fb8aa3b, v26
	v_exp_f32_e32 v29, v26
	v_mul_f32_e32 v26, 0x3d372713, v24
	v_mul_f32_e32 v26, v26, v24
	v_mov_b32_e32 v28, v24
	v_fmac_f32_e32 v28, v26, v28
	v_mul_f32_e32 v26, 0x3f4c422a, v28
	v_add_f32_e32 v26, v26, v26
	v_mul_f32_e32 v26, 0x3fb8aa3b, v26
	v_exp_f32_e32 v28, v26
	v_add_f32_e32 v26, 1.0, v31
	v_mul_f32_e32 v105, v32, v26
	v_lshlrev_b32_e32 v35, 16, v27
	v_pk_add_f32 v[28:29], v[28:29], 1.0 op_sel_hi:[1,0]
	v_fmac_f32_e32 v30, v86, v86
	v_div_scale_f32 v26, s[2:3], v29, v29, 2.0
	v_rcp_f32_e32 v31, v26
	v_fmac_f32_e32 v30, v87, v87
	v_fmac_f32_e32 v30, v100, v100
	v_fmac_f32_e32 v30, v101, v101
	v_fma_f32 v32, -v26, v31, 1.0
	v_fmac_f32_e32 v31, v32, v31
	v_div_scale_f32 v32, vcc, 2.0, v29, 2.0
	v_mul_f32_e32 v33, v32, v31
	v_fma_f32 v34, -v26, v33, v32
	v_fmac_f32_e32 v33, v34, v31
	v_fma_f32 v26, -v26, v33, v32
	v_div_scale_f32 v32, s[2:3], v28, v28, 2.0
	v_rcp_f32_e32 v34, v32
	v_div_fmas_f32 v26, v26, v31, v33
	v_div_fixup_f32 v29, v26, v29, 2.0
	v_fmac_f32_e32 v30, v102, v102
	v_fma_f32 v26, -v32, v34, 1.0
	v_fmac_f32_e32 v34, v26, v34
	v_div_scale_f32 v26, vcc, 2.0, v28, 2.0
	v_mul_f32_e32 v31, v26, v34
	v_fma_f32 v33, -v32, v31, v26
	v_fmac_f32_e32 v31, v33, v34
	v_fma_f32 v26, -v32, v31, v26
	v_div_fmas_f32 v26, v26, v34, v31
	v_div_fixup_f32 v28, v26, v28, 2.0
	v_mul_f32_e32 v26, 0x3d372713, v35
	v_and_b32_e32 v34, 0xffff0000, v27
	v_mul_f32_e32 v26, v26, v35
	v_mov_b32_e32 v27, v35
	v_fmac_f32_e32 v27, v26, v27
	v_mul_f32_e32 v26, 0x3f4c422a, v27
	v_add_f32_e32 v26, v26, v26
	v_mul_f32_e32 v26, 0x3fb8aa3b, v26
	v_exp_f32_e32 v27, v26
	v_mul_f32_e32 v26, 0x3d372713, v34
	v_mul_f32_e32 v26, v26, v34
	v_mov_b32_e32 v31, v34
	v_fmac_f32_e32 v31, v26, v31
	v_mul_f32_e32 v26, 0x3f4c422a, v31
	v_add_f32_e32 v26, v26, v26
	v_mul_f32_e32 v26, 0x3fb8aa3b, v26
	v_exp_f32_e32 v26, v26
	v_pk_add_f32 v[28:29], v[28:29], 1.0 op_sel_hi:[1,0] neg_lo:[1,0] neg_hi:[1,0]
	v_fmac_f32_e32 v30, v103, v103
	v_pk_mul_f32 v[24:25], v[24:25], 0.5 op_sel_hi:[1,0]
	v_pk_add_f32 v[28:29], v[28:29], 1.0 op_sel_hi:[1,0]
	v_fmac_f32_e32 v30, v104, v104
	v_pk_mul_f32 v[36:37], v[24:25], v[28:29]
	v_fmac_f32_e32 v30, v105, v105
	v_pk_add_f32 v[24:25], v[26:27], 1.0 op_sel_hi:[1,0]
	v_pk_mul_f32 v[26:27], v[36:37], v[36:37]
	v_div_scale_f32 v38, s[2:3], v25, v25, 2.0
	v_add_f32_e32 v27, v27, v30
	v_add_f32_e32 v49, v26, v27
	ds_read_b128 v[26:29], v210 offset:12304
	ds_read_b128 v[30:33], v210 offset:12288
	v_rcp_f32_e32 v39, v38
	v_pk_mul_f32 v[34:35], v[34:35], 0.5 op_sel_hi:[1,0]
	v_fma_f32 v106, -v38, v39, 1.0
	v_fmac_f32_e32 v39, v106, v39
	v_div_scale_f32 v106, vcc, 2.0, v25, 2.0
	v_mul_f32_e32 v107, v106, v39
	v_fma_f32 v108, -v38, v107, v106
	v_fmac_f32_e32 v107, v108, v39
	v_fma_f32 v38, -v38, v107, v106
	v_div_scale_f32 v106, s[2:3], v24, v24, 2.0
	v_rcp_f32_e32 v108, v106
	v_div_fmas_f32 v38, v38, v39, v107
	v_div_fixup_f32 v25, v38, v25, 2.0
	v_fma_f32 v38, -v106, v108, 1.0
	v_fmac_f32_e32 v108, v38, v108
	v_div_scale_f32 v38, vcc, 2.0, v24, 2.0
	v_mul_f32_e32 v39, v38, v108
	v_fma_f32 v107, -v106, v39, v38
	v_fmac_f32_e32 v39, v107, v108
	v_fma_f32 v38, -v106, v39, v38
	v_div_fmas_f32 v38, v38, v108, v39
	v_div_fixup_f32 v24, v38, v24, 2.0
	v_pk_add_f32 v[24:25], v[24:25], 1.0 op_sel_hi:[1,0] neg_lo:[1,0] neg_hi:[1,0]
	s_nop 0
	v_pk_add_f32 v[24:25], v[24:25], 1.0 op_sel_hi:[1,0]
	s_nop 0
	v_pk_mul_f32 v[38:39], v[34:35], v[24:25]
	s_nop 0
	v_pk_mul_f32 v[24:25], v[38:39], v[38:39]
	s_nop 0
	v_add_f32_e32 v25, v25, v49
	v_add_f32_e32 v24, v24, v25
	ds_bpermute_b32 v25, v91, v24
	v_ashrrev_i32_e32 v49, 31, v48
	s_waitcnt lgkmcnt(0)
	v_add_f32_e32 v24, v24, v25
	ds_bpermute_b32 v25, v92, v24
	s_waitcnt lgkmcnt(0)
	v_add_f32_e32 v24, v24, v25
	ds_bpermute_b32 v25, v57, v24
	s_waitcnt lgkmcnt(0)
	v_add_f32_e32 v24, v24, v25
	ds_bpermute_b32 v25, v88, v24
	s_waitcnt lgkmcnt(0)
	v_add_f32_e32 v24, v24, v25
	ds_bpermute_b32 v25, v89, v24
	s_waitcnt lgkmcnt(0)
	v_add_f32_e32 v24, v24, v25
	ds_bpermute_b32 v25, v90, v24
	s_waitcnt lgkmcnt(0)
; __device__ __forceinline__ unsigned cvt_pk_bf16(float lo, float hi) { unsigned r; asm volatile("v_cvt_pk_bf16_f32 %0, %1, %2" : "=v"(r) : "v"(lo), "v"(hi)); return r; }
; __device__ __forceinline__ float lo_f(unsigned w) { return __uint_as_float(w << 16); }
; __device__ __forceinline__ float hi_f(unsigned w) { return __uint_as_float(w & 0xffff0000u); }
; __device__ void phase_post(const Ctx& c, int l, bool ctx_full) {
;     ...
;             ss = wave_sum(ss, c.lane); const float rstd = rsqrtf(ss * (1.f / 1024.f) + EPS);
; #pragma unroll
;             for (int i = 0; i < 2; ++i) { const int cc = i * 512 + c.lane * 8;
;                 const f32x4 g0 = *(const f32x4*)(gv + cc), g1 = *(const f32x4*)(gv + cc + 4);
;                 u32x4 w;
;                 w.x = cvt_pk_bf16(fv[i * 8 + 0] * rstd * g0[0], fv[i * 8 + 1] * rstd * g0[1]); w.y = cvt_pk_bf16(fv[i * 8 + 2] * rstd * g0[2], fv[i * 8 + 3] * rstd * g0[3]);
;                 w.z = cvt_pk_bf16(fv[i * 8 + 4] * rstd * g1[0], fv[i * 8 + 5] * rstd * g1[1]); w.w = cvt_pk_bf16(fv[i * 8 + 6] * rstd * g1[2], fv[i * 8 + 7] * rstd * g1[3]);
;                 *(u32x4*)(VN + (size_t)row * 1024 + cc) = w; }
; #pragma unroll
;             for (int i = 0; i < 2; ++i) { const int cc = i * 512 + c.lane * 8;
;                 float a[8] = {0.f, 0.f, 0.f, 0.f, 0.f, 0.f, 0.f, 0.f};
; #pragma unroll
;                 for (int k = 0; k < 3; ++k) { const int tt = t + k - 1;
;                     if (tt >= 0 && tt < slen) { const bf16_t* z2 = zr + (ptrdiff_t)(k - 1) * IN_DIM;
;                         const u32x4 cg = *(const u32x4*)(z2 + OFF_CC + cc), hh = *(const u32x4*)(z2 + OFF_CH + cc);
;                         const f32x4 w0 = *(const f32x4*)(wsc + k * 1024 + cc), w1 = *(const f32x4*)(wsc + k * 1024 + cc + 4);
;                         a[0] += w0[0] * lo_f(cg.x) * lo_f(hh.x); a[1] += w0[1] * hi_f(cg.x) * hi_f(hh.x); a[2] += w0[2] * lo_f(cg.y) * lo_f(hh.y); a[3] += w0[3] * hi_f(cg.y) * hi_f(hh.y);
	v_add_f32_e32 v24, v24, v25
	v_fmamk_f32 v24, v24, 0x3a800000, v94
	v_mul_f32_e32 v25, 0x4b800000, v24
	v_cmp_gt_f32_e32 vcc, s29, v24
	s_nop 1
	v_cndmask_b32_e32 v24, v24, v25, vcc
	v_rsq_f32_e32 v24, v24
	s_nop 0
	v_mul_f32_e32 v25, 0x45800000, v24
	v_cndmask_b32_e32 v106, v24, v25, vcc
	v_mul_f32_e32 v34, v77, v106
	s_waitcnt lgkmcnt(0)
	v_mul_f32_e32 v30, v30, v34
	v_mul_f32_e32 v34, v79, v106
	v_mul_f32_e32 v31, v31, v34
	v_cvt_pk_bf16_f32 v30, v30, v31
	v_mul_f32_e32 v31, v85, v106
	v_mul_f32_e32 v31, v32, v31
	v_mul_f32_e32 v32, v84, v106
	v_mul_f32_e32 v32, v33, v32
	v_cvt_pk_bf16_f32 v31, v31, v32
	v_mul_f32_e32 v32, v86, v106
	v_mul_f32_e32 v26, v26, v32
	v_mul_f32_e32 v32, v87, v106
	v_lshlrev_b64 v[24:25], 11, v[48:49]
	v_mul_f32_e32 v27, v27, v32
	v_cvt_pk_bf16_f32 v32, v26, v27
	v_mul_f32_e32 v26, v100, v106
	v_mul_f32_e32 v27, v101, v106
	v_lshl_add_u64 v[84:85], v[68:69], 0, v[24:25]
	v_mul_f32_e32 v26, v28, v26
	v_mul_f32_e32 v27, v29, v27
	v_cvt_pk_bf16_f32 v33, v26, v27
	global_store_dwordx4 v[84:85], v[30:33], off
	ds_read_b128 v[28:31], v210 offset:14336
	s_nop 0
	ds_read_b128 v[32:35], v210 offset:14352
	v_mul_f32_e32 v27, v102, v106
	v_cndmask_b32_e64 v26, v97, v98, s[6:7]
	s_waitcnt lgkmcnt(1)
	v_mul_f32_e32 v27, v28, v27
	v_mul_f32_e32 v28, v103, v106
	v_mul_f32_e32 v28, v29, v28
	v_cvt_pk_bf16_f32 v28, v27, v28
	v_mul_f32_e32 v27, v104, v106
	v_mul_f32_e32 v29, v105, v106
	v_mul_f32_e32 v27, v30, v27
	v_mul_f32_e32 v29, v31, v29
	v_cvt_pk_bf16_f32 v29, v27, v29
	v_mul_f32_e32 v27, v37, v106
	v_mul_f32_e32 v30, v36, v106
	s_waitcnt lgkmcnt(0)
	v_mul_f32_e32 v27, v32, v27
	v_mul_f32_e32 v30, v33, v30
	v_cvt_pk_bf16_f32 v30, v27, v30
	v_mul_f32_e32 v27, v39, v106
	v_mul_f32_e32 v31, v38, v106
	v_mul_f32_e32 v27, v34, v27
	v_mul_f32_e32 v31, v35, v31
	v_cvt_pk_bf16_f32 v31, v27, v31
	v_add_u32_e32 v27, -1, v99
	v_mov_b32_e32 v36, v51
	v_mov_b32_e32 v37, v51
	global_store_dwordx4 v[84:85], v[28:31], off offset:1024
	v_cmp_lt_u32_e64 s[6:7], v27, v26
	v_mov_b64_e32 v[38:39], v[36:37]
	v_mov_b64_e32 v[84:85], v[36:37]
	v_mov_b64_e32 v[86:87], v[36:37]
	s_and_saveexec_b64 s[2:3], s[6:7]
	s_cbranch_execz .LBB0_376
	v_add_co_u32_e32 v28, vcc, 0xffffc000, v82
	s_nop 1
	v_addc_co_u32_e32 v29, vcc, -1, v83, vcc
	v_mov_b64_e32 v[28:29], v[152:153]
	v_mov_b64_e32 v[30:31], v[154:155]
	v_add_co_u32_e32 v86, vcc, 0xffffd000, v82
	v_lshlrev_b32_e32 v100, 16, v30
	v_addc_co_u32_e32 v87, vcc, -1, v83, vcc
	ds_read_b128 v[32:35], v210 offset:0
	v_mov_b64_e32 v[36:37], v[156:157]
	v_mov_b64_e32 v[38:39], v[158:159]
	ds_read_b128 v[82:85], v210 offset:16
	v_lshlrev_b32_e32 v86, 16, v28
	v_and_b32_e32 v87, 0xffff0000, v28
	v_lshlrev_b32_e32 v28, 16, v29
	v_and_b32_e32 v29, 0xffff0000, v29
	v_and_b32_e32 v101, 0xffff0000, v30
	v_lshlrev_b32_e32 v30, 16, v31
	v_and_b32_e32 v31, 0xffff0000, v31
	s_waitcnt lgkmcnt(1)
	v_pk_mul_f32 v[32:33], v[32:33], v[86:87]
	s_waitcnt lgkmcnt(1)
	v_lshlrev_b32_e32 v86, 16, v36
	v_and_b32_e32 v87, 0xffff0000, v36
	v_pk_mul_f32 v[28:29], v[34:35], v[28:29]
	v_lshlrev_b32_e32 v34, 16, v37
	v_and_b32_e32 v35, 0xffff0000, v37
	s_waitcnt lgkmcnt(0)
	v_pk_mul_f32 v[82:83], v[82:83], v[100:101]
	v_lshlrev_b32_e32 v100, 16, v38
	v_and_b32_e32 v101, 0xffff0000, v38
	v_pk_mul_f32 v[30:31], v[84:85], v[30:31]
	v_lshlrev_b32_e32 v102, 16, v39
	v_and_b32_e32 v103, 0xffff0000, v39
	v_pk_fma_f32 v[36:37], v[32:33], v[86:87], 0 op_sel_hi:[1,1,0]
	v_pk_fma_f32 v[38:39], v[28:29], v[34:35], 0 op_sel_hi:[1,1,0]
	v_pk_fma_f32 v[84:85], v[82:83], v[100:101], 0 op_sel_hi:[1,1,0]
	v_pk_fma_f32 v[86:87], v[30:31], v[102:103], 0 op_sel_hi:[1,1,0]
.LBB0_376:
	s_or_b64 exec, exec, s[2:3]
	v_cmp_lt_u32_e64 s[8:9], v99, v26
	s_and_saveexec_b64 s[2:3], s[8:9]
	s_cbranch_execz .LBB0_378
	v_lshl_add_u64 v[28:29], v[80:81], 0, v[50:51]
	v_add_co_u32_e32 v82, vcc, 0x3000, v28
	s_nop 1
	v_addc_co_u32_e32 v83, vcc, 0, v29, vcc
	v_mov_b64_e32 v[28:29], v[160:161]
	v_mov_b64_e32 v[30:31], v[162:163]
	v_mov_b64_e32 v[32:33], v[164:165]
	v_mov_b64_e32 v[34:35], v[166:167]
	ds_read_b128 v[100:103], v210 offset:4096
	ds_read_b128 v[104:107], v210 offset:4112
	s_waitcnt lgkmcnt(3)
	v_lshlrev_b32_e32 v82, 16, v28
	v_and_b32_e32 v83, 0xffff0000, v28
	v_lshlrev_b32_e32 v28, 16, v29
	v_and_b32_e32 v29, 0xffff0000, v29
	v_lshlrev_b32_e32 v110, 16, v30
	v_and_b32_e32 v111, 0xffff0000, v30
	v_lshlrev_b32_e32 v30, 16, v31
	v_and_b32_e32 v31, 0xffff0000, v31
	s_waitcnt lgkmcnt(2)
	v_lshlrev_b32_e32 v108, 16, v32
	v_and_b32_e32 v109, 0xffff0000, v32
	v_lshlrev_b32_e32 v32, 16, v33
	v_and_b32_e32 v33, 0xffff0000, v33
	v_lshlrev_b32_e32 v112, 16, v34
	v_and_b32_e32 v113, 0xffff0000, v34
	v_lshlrev_b32_e32 v34, 16, v35
	v_and_b32_e32 v35, 0xffff0000, v35
	s_waitcnt lgkmcnt(1)
	v_pk_mul_f32 v[82:83], v[100:101], v[82:83]
	v_pk_mul_f32 v[28:29], v[102:103], v[28:29]
	s_waitcnt lgkmcnt(0)
	v_pk_mul_f32 v[100:101], v[104:105], v[110:111]
	v_pk_mul_f32 v[30:31], v[106:107], v[30:31]
	v_pk_fma_f32 v[36:37], v[82:83], v[108:109], v[36:37]
	v_pk_fma_f32 v[38:39], v[28:29], v[32:33], v[38:39]
	v_pk_fma_f32 v[84:85], v[100:101], v[112:113], v[84:85]
	v_pk_fma_f32 v[86:87], v[30:31], v[34:35], v[86:87]
; __device__ __forceinline__ unsigned cvt_pk_bf16(float lo, float hi) { unsigned r; asm volatile("v_cvt_pk_bf16_f32 %0, %1, %2" : "=v"(r) : "v"(lo), "v"(hi)); return r; }
; __device__ __forceinline__ float lo_f(unsigned w) { return __uint_as_float(w << 16); }
; __device__ __forceinline__ float hi_f(unsigned w) { return __uint_as_float(w & 0xffff0000u); }
; __device__ void phase_post(const Ctx& c, int l, bool ctx_full) {
;     ...
;             for (int i = 0; i < 2; ++i) { const int cc = i * 512 + c.lane * 8;
;                 float a[8] = {0.f, 0.f, 0.f, 0.f, 0.f, 0.f, 0.f, 0.f};
; #pragma unroll
;                 for (int k = 0; k < 3; ++k) { const int tt = t + k - 1;
;                     if (tt >= 0 && tt < slen) { const bf16_t* z2 = zr + (ptrdiff_t)(k - 1) * IN_DIM;
;                         const u32x4 cg = *(const u32x4*)(z2 + OFF_CC + cc), hh = *(const u32x4*)(z2 + OFF_CH + cc);
;                         const f32x4 w0 = *(const f32x4*)(wsc + k * 1024 + cc), w1 = *(const f32x4*)(wsc + k * 1024 + cc + 4);
;                         a[0] += w0[0] * lo_f(cg.x) * lo_f(hh.x); a[1] += w0[1] * hi_f(cg.x) * hi_f(hh.x); a[2] += w0[2] * lo_f(cg.y) * lo_f(hh.y); a[3] += w0[3] * hi_f(cg.y) * hi_f(hh.y);
;                         a[4] += w1[0] * lo_f(cg.z) * lo_f(hh.z); a[5] += w1[1] * hi_f(cg.z) * hi_f(hh.z); a[6] += w1[2] * lo_f(cg.w) * lo_f(hh.w); a[7] += w1[3] * hi_f(cg.w) * hi_f(hh.w); } }
;                 const u32x4 bg = *(const u32x4*)(zr + OFF_CB + cc);
;                 u32x4 w;
;                 w.x = cvt_pk_bf16(a[0] * lo_f(bg.x), a[1] * hi_f(bg.x)); w.y = cvt_pk_bf16(a[2] * lo_f(bg.y), a[3] * hi_f(bg.y));
;                 w.z = cvt_pk_bf16(a[4] * lo_f(bg.z), a[5] * hi_f(bg.z)); w.w = cvt_pk_bf16(a[6] * lo_f(bg.w), a[7] * hi_f(bg.w));
;                 *(u32x4*)(AM1 + (size_t)row * 1024 + cc) = w; }
.LBB0_378:
	s_or_b64 exec, exec, s[2:3]
	v_add_u32_e32 v27, 1, v99
	v_cmp_lt_u32_e64 s[10:11], v27, v26
	s_and_saveexec_b64 s[2:3], s[10:11]
	s_cbranch_execz .LBB0_380
	v_lshl_add_u64 v[26:27], v[80:81], 0, v[50:51]
	v_add_co_u32_e32 v34, vcc, 0xa000, v26
	s_nop 1
	v_addc_co_u32_e32 v35, vcc, 0, v27, vcc
	v_mov_b64_e32 v[26:27], v[168:169]
	v_mov_b64_e32 v[28:29], v[170:171]
	v_mov_b64_e32 v[30:31], v[172:173]
	v_mov_b64_e32 v[32:33], v[174:175]
	ds_read_b128 v[100:103], v210 offset:8192
	ds_read_b128 v[104:107], v210 offset:8208
	s_waitcnt lgkmcnt(3)
	v_lshlrev_b32_e32 v34, 16, v26
	v_and_b32_e32 v35, 0xffff0000, v26
	v_lshlrev_b32_e32 v26, 16, v27
	v_and_b32_e32 v27, 0xffff0000, v27
	v_lshlrev_b32_e32 v108, 16, v28
	v_and_b32_e32 v109, 0xffff0000, v28
	v_lshlrev_b32_e32 v28, 16, v29
	v_and_b32_e32 v29, 0xffff0000, v29
	s_waitcnt lgkmcnt(2)
	v_lshlrev_b32_e32 v82, 16, v30
	v_and_b32_e32 v83, 0xffff0000, v30
	v_lshlrev_b32_e32 v30, 16, v31
	v_and_b32_e32 v31, 0xffff0000, v31
	v_lshlrev_b32_e32 v110, 16, v32
	v_and_b32_e32 v111, 0xffff0000, v32
	v_lshlrev_b32_e32 v32, 16, v33
	v_and_b32_e32 v33, 0xffff0000, v33
	s_waitcnt lgkmcnt(1)
	v_pk_mul_f32 v[34:35], v[100:101], v[34:35]
	v_pk_mul_f32 v[26:27], v[102:103], v[26:27]
	s_waitcnt lgkmcnt(0)
	v_pk_mul_f32 v[100:101], v[104:105], v[108:109]
	v_pk_mul_f32 v[28:29], v[106:107], v[28:29]
	v_pk_fma_f32 v[36:37], v[34:35], v[82:83], v[36:37]
	v_pk_fma_f32 v[38:39], v[26:27], v[30:31], v[38:39]
	v_pk_fma_f32 v[84:85], v[100:101], v[110:111], v[84:85]
	v_pk_fma_f32 v[86:87], v[28:29], v[32:33], v[86:87]
.LBB0_380:
	s_or_b64 exec, exec, s[2:3]
	v_lshl_add_u64 v[26:27], v[80:81], 0, s[20:21]
	v_lshl_add_u64 v[28:29], v[26:27], 0, v[50:51]
	v_mov_b64_e32 v[100:101], v[144:145]
	v_mov_b64_e32 v[102:103], v[146:147]
	v_lshl_add_u64 v[24:25], v[70:71], 0, v[24:25]
	v_mov_b32_e32 v30, v51
	v_mov_b32_e32 v31, v51
	v_lshlrev_b32_e32 v28, 1, v56
	v_mov_b64_e32 v[32:33], v[30:31]
	v_mov_b64_e32 v[34:35], v[30:31]
	s_waitcnt lgkmcnt(0)
	v_lshlrev_b32_e32 v29, 16, v100
	v_and_b32_e32 v49, 0xffff0000, v100
	v_lshlrev_b32_e32 v77, 16, v101
	v_and_b32_e32 v79, 0xffff0000, v101
	v_lshlrev_b32_e32 v82, 16, v102
	v_mul_f32_e32 v29, v36, v29
	v_mul_f32_e32 v36, v37, v49
	v_mul_f32_e32 v37, v38, v77
	v_and_b32_e32 v83, 0xffff0000, v102
	v_lshlrev_b32_e32 v99, 16, v103
	v_and_b32_e32 v100, 0xffff0000, v103
	v_mul_f32_e32 v38, v39, v79
	v_mul_f32_e32 v39, v84, v82
	v_cvt_pk_bf16_f32 v36, v29, v36
	v_cvt_pk_bf16_f32 v37, v37, v38
	v_mul_f32_e32 v49, v85, v83
	v_mul_f32_e32 v77, v86, v99
	v_mul_f32_e32 v79, v87, v100
	v_cvt_pk_bf16_f32 v38, v39, v49
	v_cvt_pk_bf16_f32 v39, v77, v79
	global_store_dwordx4 v[24:25], v[36:39], off
	s_nop 1
	v_mov_b64_e32 v[36:37], v[30:31]
	s_and_saveexec_b64 s[2:3], s[6:7]
	s_cbranch_execz .LBB0_383
	v_mov_b32_e32 v29, v51
	v_lshl_add_u64 v[34:35], v[80:81], 0, v[28:29]
	v_add_co_u32_e32 v30, vcc, 0xffffc000, v34
	s_nop 1
	v_addc_co_u32_e32 v31, vcc, -1, v35, vcc
	v_mov_b64_e32 v[30:31], v[176:177]
	v_mov_b64_e32 v[32:33], v[178:179]
	v_add_co_u32_e32 v38, vcc, 0xffffd000, v34
	v_lshlrev_b32_e32 v86, 16, v32
	v_addc_co_u32_e32 v39, vcc, -1, v35, vcc
	ds_read_b128 v[34:37], v210 offset:2048
	v_mov_b64_e32 v[82:83], v[180:181]
	v_mov_b64_e32 v[84:85], v[182:183]
	ds_read_b128 v[100:103], v210 offset:2064
	v_lshlrev_b32_e32 v38, 16, v30
	v_and_b32_e32 v39, 0xffff0000, v30
	v_lshlrev_b32_e32 v30, 16, v31
	v_and_b32_e32 v31, 0xffff0000, v31
	v_and_b32_e32 v87, 0xffff0000, v32
	v_lshlrev_b32_e32 v32, 16, v33
	v_and_b32_e32 v33, 0xffff0000, v33
	s_waitcnt lgkmcnt(1)
	v_pk_mul_f32 v[34:35], v[34:35], v[38:39]
	s_waitcnt lgkmcnt(1)
	v_lshlrev_b32_e32 v38, 16, v82
	v_and_b32_e32 v39, 0xffff0000, v82
	v_pk_mul_f32 v[36:37], v[36:37], v[30:31]
	v_lshlrev_b32_e32 v82, 16, v83
	v_and_b32_e32 v83, 0xffff0000, v83
	s_waitcnt lgkmcnt(0)
	v_pk_mul_f32 v[86:87], v[100:101], v[86:87]
	v_lshlrev_b32_e32 v100, 16, v84
	v_and_b32_e32 v101, 0xffff0000, v84
	v_pk_mul_f32 v[102:103], v[102:103], v[32:33]
	v_lshlrev_b32_e32 v84, 16, v85
	v_and_b32_e32 v85, 0xffff0000, v85
	v_pk_fma_f32 v[30:31], v[34:35], v[38:39], 0 op_sel_hi:[1,1,0]
	v_pk_fma_f32 v[32:33], v[36:37], v[82:83], 0 op_sel_hi:[1,1,0]
	v_pk_fma_f32 v[34:35], v[86:87], v[100:101], 0 op_sel_hi:[1,1,0]
	v_pk_fma_f32 v[36:37], v[102:103], v[84:85], 0 op_sel_hi:[1,1,0]
	s_or_b64 exec, exec, s[2:3]
	s_and_saveexec_b64 s[2:3], s[8:9]
	s_cbranch_execnz .LBB0_384

; __device__ __forceinline__ float lo_f(unsigned w) { return __uint_as_float(w << 16); }
; __device__ __forceinline__ float hi_f(unsigned w) { return __uint_as_float(w & 0xffff0000u); }
; __device__ void phase_post(const Ctx& c, int l, bool ctx_full) {
;     ...
;             for (int i = 0; i < 2; ++i) { const int cc = i * 512 + c.lane * 8;
;                 float a[8] = {0.f, 0.f, 0.f, 0.f, 0.f, 0.f, 0.f, 0.f};
; #pragma unroll
;                 for (int k = 0; k < 3; ++k) { const int tt = t + k - 1;
;                     if (tt >= 0 && tt < slen) { const bf16_t* z2 = zr + (ptrdiff_t)(k - 1) * IN_DIM;
;                         const u32x4 cg = *(const u32x4*)(z2 + OFF_CC + cc), hh = *(const u32x4*)(z2 + OFF_CH + cc);
;                         const f32x4 w0 = *(const f32x4*)(wsc + k * 1024 + cc), w1 = *(const f32x4*)(wsc + k * 1024 + cc + 4);
;                         a[0] += w0[0] * lo_f(cg.x) * lo_f(hh.x); a[1] += w0[1] * hi_f(cg.x) * hi_f(hh.x); a[2] += w0[2] * lo_f(cg.y) * lo_f(hh.y); a[3] += w0[3] * hi_f(cg.y) * hi_f(hh.y);
;                         a[4] += w1[0] * lo_f(cg.z) * lo_f(hh.z); a[5] += w1[1] * hi_f(cg.z) * hi_f(hh.z); a[6] += w1[2] * lo_f(cg.w) * lo_f(hh.w); a[7] += w1[3] * hi_f(cg.w) * hi_f(hh.w); } }
.LBB0_384:
	v_mov_b32_e32 v29, v51
	v_lshl_add_u64 v[38:39], v[80:81], 0, v[28:29]
	v_add_co_u32_e32 v38, vcc, 0x3000, v38
	s_nop 1
	v_addc_co_u32_e32 v39, vcc, 0, v39, vcc
	v_mov_b64_e32 v[82:83], v[184:185]
	v_mov_b64_e32 v[84:85], v[186:187]
	v_mov_b64_e32 v[100:101], v[188:189]
	v_mov_b64_e32 v[102:103], v[190:191]
	ds_read_b128 v[104:107], v210 offset:6144
	ds_read_b128 v[108:111], v210 offset:6160
	s_waitcnt lgkmcnt(3)
	v_lshlrev_b32_e32 v38, 16, v82
	v_and_b32_e32 v39, 0xffff0000, v82
	v_lshlrev_b32_e32 v82, 16, v83
	v_and_b32_e32 v83, 0xffff0000, v83
	v_lshlrev_b32_e32 v112, 16, v84
	v_and_b32_e32 v113, 0xffff0000, v84
	v_lshlrev_b32_e32 v84, 16, v85
	v_and_b32_e32 v85, 0xffff0000, v85
	s_waitcnt lgkmcnt(2)
	v_lshlrev_b32_e32 v86, 16, v100
	v_and_b32_e32 v87, 0xffff0000, v100
	v_lshlrev_b32_e32 v100, 16, v101
	v_and_b32_e32 v101, 0xffff0000, v101
	v_lshlrev_b32_e32 v114, 16, v102
	v_and_b32_e32 v115, 0xffff0000, v102
	v_lshlrev_b32_e32 v102, 16, v103
	v_and_b32_e32 v103, 0xffff0000, v103
	s_waitcnt lgkmcnt(1)
	v_pk_mul_f32 v[38:39], v[104:105], v[38:39]
	v_pk_mul_f32 v[82:83], v[106:107], v[82:83]
	s_waitcnt lgkmcnt(0)
	v_pk_mul_f32 v[104:105], v[108:109], v[112:113]
	v_pk_mul_f32 v[84:85], v[110:111], v[84:85]
	v_pk_fma_f32 v[30:31], v[38:39], v[86:87], v[30:31]
	v_pk_fma_f32 v[32:33], v[82:83], v[100:101], v[32:33]
	v_pk_fma_f32 v[34:35], v[104:105], v[114:115], v[34:35]
	v_pk_fma_f32 v[36:37], v[84:85], v[102:103], v[36:37]
	s_or_b64 exec, exec, s[2:3]
	s_and_saveexec_b64 s[2:3], s[10:11]
	s_cbranch_execz .LBB0_369
.LBB0_385:
	v_mov_b32_e32 v29, v51
	v_lshl_add_u64 v[38:39], v[80:81], 0, v[28:29]
	v_add_co_u32_e32 v38, vcc, 0xa000, v38
	s_nop 1
	v_addc_co_u32_e32 v39, vcc, 0, v39, vcc
	v_mov_b64_e32 v[80:81], v[192:193]
	v_mov_b64_e32 v[82:83], v[194:195]
	v_mov_b64_e32 v[84:85], v[196:197]
	v_mov_b64_e32 v[86:87], v[198:199]
	ds_read_b128 v[100:103], v210 offset:10240
	ds_read_b128 v[104:107], v210 offset:10256
	s_waitcnt lgkmcnt(3)
	v_lshlrev_b32_e32 v38, 16, v80
	v_and_b32_e32 v39, 0xffff0000, v80
	v_lshlrev_b32_e32 v80, 16, v81
	v_and_b32_e32 v81, 0xffff0000, v81
	v_lshlrev_b32_e32 v110, 16, v82
	v_and_b32_e32 v111, 0xffff0000, v82
	v_lshlrev_b32_e32 v82, 16, v83
	v_and_b32_e32 v83, 0xffff0000, v83
	s_waitcnt lgkmcnt(2)
	v_lshlrev_b32_e32 v108, 16, v84
	v_and_b32_e32 v109, 0xffff0000, v84
	v_lshlrev_b32_e32 v84, 16, v85
	v_and_b32_e32 v85, 0xffff0000, v85
	v_lshlrev_b32_e32 v112, 16, v86
	v_and_b32_e32 v113, 0xffff0000, v86
	v_lshlrev_b32_e32 v86, 16, v87
	v_and_b32_e32 v87, 0xffff0000, v87
	s_waitcnt lgkmcnt(1)
	v_pk_mul_f32 v[38:39], v[100:101], v[38:39]
	v_pk_mul_f32 v[80:81], v[102:103], v[80:81]
	s_waitcnt lgkmcnt(0)
	v_pk_mul_f32 v[100:101], v[104:105], v[110:111]
	v_pk_mul_f32 v[82:83], v[106:107], v[82:83]
	v_pk_fma_f32 v[30:31], v[38:39], v[108:109], v[30:31]
	v_pk_fma_f32 v[32:33], v[80:81], v[84:85], v[32:33]
	v_pk_fma_f32 v[34:35], v[100:101], v[112:113], v[34:35]
	v_pk_fma_f32 v[36:37], v[82:83], v[86:87], v[36:37]
	s_branch .LBB0_369

;     __device__ __forceinline__ bf16_t* bfp(size_t off) const { return (bf16_t*)(ws + off); }
;     __device__ __forceinline__ float* fp(size_t off) const { return (float*)(ws + off); }
; __device__ void phase_post(const Ctx& c, int l, bool ctx_full) {
;     const KParams pk = c.p;
;     const bf16_t* Z = c.bfp(WS_Z);
;     bf16_t* Qo = c.bfp(WS_Q); bf16_t* Ko = c.bfp(WS_K); bf16_t* Vo = c.bfp(WS_V); bf16_t* VN = c.bfp(WS_VN);
;     bf16_t* AM0 = c.bfp(WS_AM); bf16_t* AM1 = c.bfp(WS_AM + (size_t)TT * 1024 * 2);
;     const int l16 = c.lane & 15, grp = c.lane >> 4, axis = l16 >> 3, fb = (l16 & 3) * 8;
;     const bool firsth = (l16 & 4) == 0;
;     float gqo[8], gqp[8], gko[8], gkp[8];
; #pragma unroll
;     for (int i = 0; i < 8; ++i) { gqo[i] = pk->in[8][l * 128 + 8 * l16 + i]; gqp[i] = pk->in[8][l * 128 + 8 * (l16 ^ 4) + i]; gko[i] = pk->in[9][l * 128 + 8 * l16 + i]; gkp[i] = pk->in[9][l * 128 + 8 * (l16 ^ 4) + i]; }
;     const float* rope = c.fp(WS_ROPE);
;     const float* kvp = c.fp(WS_AM + (size_t)2 * TT * 1024 * 2);
;     const float* gv = pk->in[12] + l * 1024; const float* wsc = pk->in[13] + (size_t)l * 3 * 1024;
.LBB0_1443:
	s_mov_b32 s2, 0
	s_waitcnt lgkmcnt(0)
	s_barrier
	s_mov_b32 s3, s33
	v_mbcnt_lo_u32_b32 v0, -1, s2
	v_mbcnt_hi_u32_b32 v0, -1, v0
	v_readfirstlane_b32 s2, v217
	v_lshl_or_b32 v32, s3, 6, v0
	s_mov_b64 s[4:5], s[0:1]
	v_ashrrev_i32_e32 v0, 6, v32
	v_lshl_add_u32 v52, s2, 3, v0
	s_movk_i32 s2, 0x2400
	v_cmp_gt_i32_e32 vcc, s2, v52
	s_and_saveexec_b64 s[10:11], vcc
	s_cbranch_execz .LBB0_1470
	s_load_dwordx2 s[2:3], s[4:5], 0xc0
	v_and_b32_e32 v33, 63, v32
	s_load_dwordx4 s[16:19], s[4:5], 0x40
	s_load_dwordx4 s[20:23], s[4:5], 0x60
	v_lshlrev_b32_e32 v54, 3, v33
	v_and_b32_e32 v35, 0x78, v54
	v_mov_b32_e32 v0, 0x78
	v_lshlrev_b32_e32 v56, 2, v35
	v_bitop3_b32 v0, v54, 32, v0 bitop3:0x6c
	v_lshlrev_b32_e32 v36, 2, v0
	s_waitcnt lgkmcnt(0)
	global_load_dwordx4 v[0:3], v56, s[16:17] offset:512
	global_load_dwordx4 v[4:7], v56, s[18:19] offset:512
	global_load_dwordx4 v[8:11], v56, s[16:17] offset:528
	global_load_dwordx4 v[12:15], v56, s[18:19] offset:528
	global_load_dwordx4 v[16:19], v36, s[16:17] offset:512
	global_load_dwordx4 v[20:23], v36, s[18:19] offset:512
	global_load_dwordx4 v[24:27], v36, s[16:17] offset:528
	global_load_dwordx4 v[28:31], v36, s[18:19] offset:528
	s_add_u32 s14, s2, 0x18d78000
	s_addc_u32 s15, s3, 0
	v_and_b32_e32 v34, 4, v32
	s_add_u32 s16, s2, 0x3197b600
	v_cmp_eq_u32_e64 s[4:5], 0, v34
	s_addc_u32 s17, s3, 0
	v_lshlrev_b32_e32 v34, 4, v33
	v_mov_b32_e32 v57, 0
	v_bfe_u32 v38, v32, 4, 2
	s_add_u32 s8, s2, 0x2ad78000
	v_and_b32_e32 v36, 48, v34
	s_addc_u32 s9, s3, 0
	v_and_or_b32 v39, v54, 64, v36
	v_lshlrev_b32_e32 v36, 9, v38
	v_mov_b32_e32 v37, v57
	v_lshl_add_u64 v[36:37], s[8:9], 0, v[36:37]
	v_lshl_add_u64 v[58:59], v[36:37], 0, v[56:57]
	v_lshlrev_b32_e32 v56, 8, v38
	s_add_u32 s22, s22, 0x3000
	v_lshl_add_u64 v[36:37], s[2:3], 0, v[56:57]
	v_lshlrev_b32_e32 v56, 1, v35
	s_addc_u32 s23, s23, 0
	v_lshl_add_u64 v[36:37], v[36:37], 0, v[56:57]
	s_mov_b64 s[26:27], 0x2f578000
	v_mov_b32_e32 v35, v57
	v_lshlrev_b32_e32 v56, 5, v33
	s_add_u32 s20, s20, 0x1000
	v_lshl_add_u64 v[60:61], v[36:37], 0, s[26:27]
	v_lshlrev_b32_e32 v36, 2, v33
	v_lshl_add_u64 v[34:35], s[2:3], 0, v[34:35]
	v_or_b32_e32 v66, 0x200, v54
	v_lshl_add_u64 v[82:83], s[8:9], 0, v[56:57]
	s_mov_b64 s[8:9], 0x30778000
	s_addc_u32 s21, s21, 0
	v_xor_b32_e32 v55, 32, v36
	v_xor_b32_e32 v67, 16, v36
	v_xor_b32_e32 v118, 8, v36
	v_xor_b32_e32 v119, 4, v36
	s_mov_b64 s[26:27], 0x2fe78000
	v_xor_b32_e32 v120, 0x80, v36
	v_xor_b32_e32 v121, 64, v36
	v_lshlrev_b32_e32 v36, 2, v66
	v_mov_b32_e32 v37, v57
	v_lshl_add_u64 v[84:85], v[34:35], 0, s[8:9]
	s_mov_b64 s[8:9], 0x29b78000
	s_movk_i32 s74, 0x7000
	v_lshlrev_b32_e32 v32, 4, v32
	v_lshl_add_u64 v[62:63], v[34:35], 0, s[26:27]
	v_lshl_add_u64 v[68:69], s[20:21], 0, v[36:37]
	v_lshl_add_u64 v[76:77], s[22:23], 0, v[36:37]
	v_lshl_add_u64 v[86:87], v[34:35], 0, s[8:9]
	v_mad_i64_i32 v[34:35], s[8:9], v52, s74, 0
	v_and_b32_e32 v36, 0xf0, v32
	v_or_b32_e32 v34, v34, v36
	s_mov_b64 s[6:7], 0x18d78000
	v_ashrrev_i32_e32 v53, 31, v52
	v_lshl_add_u64 v[32:33], s[2:3], 0, v[34:35]
	v_lshl_add_u64 v[88:89], v[32:33], 0, s[6:7]
	v_lshlrev_b64 v[32:33], 12, v[52:53]
	v_lshl_add_u64 v[70:71], s[22:23], 0, v[56:57]
	s_lshl_b32 s22, s38, 3
	v_or_b32_e32 v32, v32, v36
	s_mov_b64 s[24:25], 0x1000
	v_lshlrev_b32_e32 v40, 7, v38
	v_lshl_add_u64 v[64:65], s[20:21], 0, v[56:57]
	s_mov_b64 s[20:21], 0x2000
	s_ashr_i32 s23, s22, 31
	v_lshl_add_u64 v[32:33], s[2:3], 0, v[32:33]
	s_mov_b64 s[2:3], 0x2d178000
	s_mov_b64 s[18:19], 0x3000
	v_lshl_add_u64 v[72:73], v[70:71], 0, s[24:25]
	v_lshl_add_u64 v[74:75], v[70:71], 0, s[20:21]
	v_lshl_add_u64 v[78:79], v[76:77], 0, s[24:25]
	v_lshl_add_u64 v[80:81], v[76:77], 0, s[20:21]
	s_mul_hi_i32 s43, s22, 0x7000
	v_lshl_add_u64 v[90:91], v[32:33], 0, s[2:3]
	s_lshl_b64 s[24:25], s[22:23], 12
	s_mov_b64 s[26:27], 0
	s_movk_i32 s23, 0x1fff
	s_movk_i32 s75, 0x2000
	s_movk_i32 s76, 0x7ff
	v_lshlrev_b32_e32 v122, 2, v39
	s_movk_i32 s77, 0x900
	s_mov_b64 s[28:29], 0x400000
	s_mov_b64 s[30:31], 0x800000
	s_mov_b64 s[34:35], 0xc00000
	s_mov_b64 s[44:45], 0x1000000
	s_mov_b64 s[46:47], 0x1400000
	s_mov_b64 s[48:49], 0x1800000
	s_mov_b64 s[50:51], 0x1c00000
	v_lshlrev_b32_e32 v123, 1, v40
	v_mov_b32_e32 v124, 0x358637bd
	s_mov_b32 s78, 0x800000
	s_mov_b64 s[52:53], 0x400
	s_mov_b64 s[54:55], 0x400800
	s_mov_b64 s[56:57], 0x800800
	s_mov_b64 s[58:59], 0xc00800
	s_mov_b32 s79, 0xc00000
	s_mov_b64 s[60:61], 0x1000800
	s_mov_b32 s80, 0x1000000
	s_mov_b64 s[62:63], 0x1400800
	s_mov_b32 s81, 0x1400000
	s_mov_b64 s[64:65], 0x1800800
	s_mov_b32 s82, 0x1800000
	s_mov_b64 s[66:67], 0x1c00800
	s_mov_b32 s83, 0x1c00000
	s_mov_b64 s[68:69], 0x3800
	s_mov_b64 s[70:71], 0x2800
	s_movk_i32 s85, 0x23ff
	v_mov_b32_e32 v125, 0xff
	v_mov_b32_e32 v126, 0x7ff
	v_mbcnt_lo_u32_b32 v245, -1, 0
	v_mbcnt_hi_u32_b32 v245, -1, v245
	v_lshlrev_b32_e32 v245, 5, v245
	global_load_dwordx4 v[148:151], v[70:71], off
	global_load_dwordx4 v[152:155], v[70:71], off offset:16
	global_load_dwordx4 v[156:159], v[70:71], off offset:2048
	global_load_dwordx4 v[160:163], v[70:71], off offset:2064
	global_load_dwordx4 v[164:167], v[72:73], off
	global_load_dwordx4 v[168:171], v[72:73], off offset:16
	global_load_dwordx4 v[172:175], v[72:73], off offset:2048
	global_load_dwordx4 v[176:179], v[72:73], off offset:2064
	s_waitcnt vmcnt(0)
	ds_write_b128 v245, v[148:151]
	ds_write_b128 v245, v[152:155] offset:16
	ds_write_b128 v245, v[156:159] offset:2048
	ds_write_b128 v245, v[160:163] offset:2064
	ds_write_b128 v245, v[164:167] offset:4096
	ds_write_b128 v245, v[168:171] offset:4112
	ds_write_b128 v245, v[172:175] offset:6144
	ds_write_b128 v245, v[176:179] offset:6160
	s_waitcnt lgkmcnt(0)
	global_load_dwordx4 v[148:151], v[74:75], off
	global_load_dwordx4 v[152:155], v[74:75], off offset:16
	global_load_dwordx4 v[156:159], v[74:75], off offset:2048
	global_load_dwordx4 v[160:163], v[74:75], off offset:2064
	global_load_dwordx4 v[164:167], v[64:65], off
	global_load_dwordx4 v[168:171], v[64:65], off offset:16
	global_load_dwordx4 v[172:175], v[64:65], off offset:2048
	global_load_dwordx4 v[176:179], v[64:65], off offset:2064
	s_waitcnt vmcnt(0)
	ds_write_b128 v245, v[148:151] offset:8192
	ds_write_b128 v245, v[152:155] offset:8208
	ds_write_b128 v245, v[156:159] offset:10240
	ds_write_b128 v245, v[160:163] offset:10256
	ds_write_b128 v245, v[164:167] offset:12288
	ds_write_b128 v245, v[168:171] offset:12304
	ds_write_b128 v245, v[172:175] offset:14336
	ds_write_b128 v245, v[176:179] offset:14352
	s_waitcnt lgkmcnt(0)
	s_branch .LBB0_1447

; __device__ void phase_post(const Ctx& c, int l, bool ctx_full) {
;     ...
;     for (int row = c.bid * 8 + c.wave; row < TT; row += c.G * 8) {
;         const bool lat = row < TL; int b, t, slen;
;         if (lat) { b = row >> 11; t = row & 2047; slen = SEQL; } else { b = (row - TL) >> 8; t = (row - TL) & 255; slen = CTXL; }
;         const bool full = lat || ctx_full;
;         const bf16_t* zr = Z + (size_t)row * IN_DIM;
;         float cs[8], sn[8];
;         if (lat) { const float* rp = rope + ((size_t)t * 64 + axis * 32 + fb) * 2;
; #pragma unroll
;             for (int i = 0; i < 4; ++i) { const f32x4 v = *(const f32x4*)(rp + i * 4); cs[2 * i] = v[0]; sn[2 * i] = v[1]; cs[2 * i + 1] = v[2]; sn[2 * i + 1] = v[3]; } }
;         else {
; #pragma unroll
;             for (int i = 0; i < 8; ++i) { cs[i] = 1.f; sn[i] = 0.f; } }
;         const size_t kvrow = (size_t)b * SKV + (lat ? t : SEQL + t);
;         for (int p = full ? 0 : 4; p < 5; ++p) {
;             const int hd = 4 * p + grp;
;             u32x4 raw;
;             if (full) raw = *(const u32x4*)(zr + hd * 128 + 8 * l16);
;             else raw = kv_share8(kvp + (size_t)(row - TL) * 1024 + grp * 128 + 8 * l16);
.LBB0_1447:
	v_cmp_gt_i32_e64 s[6:7], s75, v52
	v_cmp_lt_i32_e32 vcc, s23, v52
	v_mov_b32_e32 v48, 4
	v_cndmask_b32_e64 v32, v125, v126, s[6:7]
	v_and_b32_e32 v127, v32, v52
	v_mov_b32_e32 v32, 1.0
	v_mov_b32_e32 v33, 0
	v_mov_b32_e32 v35, 0
	v_mov_b32_e32 v37, 0
	v_mov_b32_e32 v39, 0
	v_mov_b32_e32 v41, 0
	v_mov_b32_e32 v43, 0
	v_mov_b32_e32 v45, 0
	v_mov_b32_e32 v47, 0
	v_mov_b32_e32 v34, 1.0
	v_mov_b32_e32 v36, 1.0
	v_mov_b32_e32 v38, 1.0
	v_mov_b32_e32 v40, 1.0
	v_mov_b32_e32 v42, 1.0
	v_mov_b32_e32 v44, 1.0
	v_mov_b32_e32 v46, 1.0
	s_and_saveexec_b64 s[2:3], s[6:7]
	s_cbranch_execz .LBB0_1449
	v_mov_b32_e32 v242, v123
	v_mov_b32_e32 v243, 0
	v_lshl_add_u64 v[244:245], v[88:89], 0, v[242:243]
	v_mov_b32_e32 v242, 0x1000
	v_lshl_add_u64 v[234:235], v[244:245], 0, v[242:243]
	v_mov_b32_e32 v242, 0x3000
	v_lshl_add_u64 v[236:237], v[244:245], 0, v[242:243]
	v_mov_b32_e32 v242, 0x7000
	v_lshl_add_u64 v[240:241], v[236:237], 0, v[242:243]
	v_mov_b32_e32 v242, 0xffff9000
	v_mov_b32_e32 v243, -1
	v_lshl_add_u64 v[238:239], v[236:237], 0, v[242:243]
	global_load_dwordx4 v[148:151], v[234:235], off offset:-4096
	global_load_dwordx4 v[152:155], v[234:235], off offset:-3072
	global_load_dwordx4 v[156:159], v[234:235], off offset:-2048
	global_load_dwordx4 v[160:163], v[234:235], off offset:-1024
	global_load_dwordx4 v[164:167], v[234:235], off
	global_load_dwordx4 v[168:171], v[236:237], off offset:-4096
	global_load_dwordx4 v[172:175], v[236:237], off offset:-3072
	global_load_dwordx4 v[176:179], v[236:237], off offset:-2048
	global_load_dwordx4 v[180:183], v[236:237], off offset:-1024
	global_load_dwordx4 v[192:195], v[236:237], off
	global_load_dwordx4 v[196:199], v[236:237], off offset:2048
	global_load_dwordx4 v[218:221], v[236:237], off offset:1024
	global_load_dwordx4 v[222:225], v[236:237], off offset:3072
	global_load_dwordx4 v[184:187], v[238:239], off
	global_load_dwordx4 v[188:191], v[238:239], off offset:2048
	global_load_dwordx4 v[208:211], v[238:239], off offset:1024
	global_load_dwordx4 v[212:215], v[238:239], off offset:3072
	global_load_dwordx4 v[200:203], v[240:241], off
	global_load_dwordx4 v[204:207], v[240:241], off offset:2048
	global_load_dwordx4 v[226:229], v[240:241], off offset:1024
	global_load_dwordx4 v[230:233], v[240:241], off offset:3072
	v_lshlrev_b32_e32 v245, 2, v54
	v_lshl_or_b32 v44, v127, 9, v122
	global_load_dwordx4 v[32:35], v44, s[16:17]
	global_load_dwordx4 v[36:39], v44, s[16:17] offset:16
	global_load_dwordx4 v[40:43], v44, s[16:17] offset:32
	s_nop 0
	global_load_dwordx4 v[44:47], v44, s[16:17] offset:48
	v_mov_b32_e32 v48, 0
	s_waitcnt vmcnt(0)

; __device__ __forceinline__ float lo_f(unsigned w) { return __uint_as_float(w << 16); }
; __device__ __forceinline__ float hi_f(unsigned w) { return __uint_as_float(w & 0xffff0000u); }
; __device__ void phase_post(const Ctx& c, int l, bool ctx_full) {
;     ...
;         if (full) {
;             float fv[16]; float ss = 0.f;
; #pragma unroll
;             for (int i = 0; i < 2; ++i) { const int cc = i * 512 + c.lane * 8;
;                 const u32x4 zv = *(const u32x4*)(zr + OFF_GV + cc);
;                 fv[i * 8 + 0] = gelu_tanh(lo_f(zv.x)); fv[i * 8 + 1] = gelu_tanh(hi_f(zv.x)); fv[i * 8 + 2] = gelu_tanh(lo_f(zv.y)); fv[i * 8 + 3] = gelu_tanh(hi_f(zv.y));
;                 fv[i * 8 + 4] = gelu_tanh(lo_f(zv.z)); fv[i * 8 + 5] = gelu_tanh(hi_f(zv.z)); fv[i * 8 + 6] = gelu_tanh(lo_f(zv.w)); fv[i * 8 + 7] = gelu_tanh(hi_f(zv.w));
; #pragma unroll
;                 for (int j = 0; j < 8; ++j) ss += fv[i * 8 + j] * fv[i * 8 + j]; }
.LBB0_1461:
	s_or_saveexec_b64 s[72:73], s[2:3]
	v_ashrrev_i32_e32 v53, 31, v52
	s_xor_b64 exec, exec, s[72:73]
	s_cbranch_execz .LBB0_1446
	v_mov_b64_e32 v[32:33], s[14:15]
	v_mad_i64_i32 v[40:41], s[2:3], v52, s74, v[32:33]
	v_lshlrev_b32_e32 v56, 1, v54
	v_lshl_add_u64 v[42:43], v[40:41], 0, v[56:57]
	v_add_co_u32_e32 v32, vcc, 0x2000, v42
	s_nop 1
	v_addc_co_u32_e32 v33, vcc, 0, v43, vcc
	v_mov_b64_e32 v[36:37], v[168:169]
	v_mov_b64_e32 v[38:39], v[170:171]
	v_lshl_add_u64 v[32:33], v[42:43], 0, s[20:21]
	v_mov_b64_e32 v[32:33], v[172:173]
	v_mov_b64_e32 v[34:35], v[174:175]
	v_lshlrev_b32_e32 v44, 16, v36
	v_and_b32_e32 v36, 0xffff0000, v36
	v_mul_f32_e32 v47, 0x3d372713, v44
	v_lshlrev_b32_e32 v45, 16, v37
	v_mul_f32_e32 v49, 0x3d372713, v36
	v_mul_f32_e32 v47, v47, v44
	v_mul_f32_e32 v48, 0.5, v44
	v_mul_f32_e32 v51, 0x3d372713, v45
	v_mul_f32_e32 v49, v49, v36
	v_fma_f32 v44, v47, v44, v44
	v_mul_f32_e32 v50, 0.5, v36
	v_mul_f32_e32 v51, v51, v45
	v_fma_f32 v36, v49, v36, v36
	v_mul_f32_e32 v44, 0x3f4c422a, v44
	v_mul_f32_e32 v92, 0.5, v45
	v_fma_f32 v45, v51, v45, v45
	v_mul_f32_e32 v36, 0x3f4c422a, v36
	v_add_f32_e32 v44, v44, v44
	v_mul_f32_e32 v45, 0x3f4c422a, v45
	v_add_f32_e32 v36, v36, v36
	v_mul_f32_e32 v44, 0x3fb8aa3b, v44
	v_add_f32_e32 v45, v45, v45
	v_mul_f32_e32 v36, 0x3fb8aa3b, v36
	v_exp_f32_e32 v44, v44
	v_mul_f32_e32 v45, 0x3fb8aa3b, v45
	v_exp_f32_e32 v36, v36
	v_exp_f32_e32 v45, v45
	v_and_b32_e32 v37, 0xffff0000, v37
	v_mul_f32_e32 v93, 0x3d372713, v37
	v_add_f32_e32 v44, 1.0, v44
	v_mul_f32_e32 v93, v93, v37
	v_add_f32_e32 v36, 1.0, v36
	v_div_scale_f32 v49, s[2:3], v44, v44, 2.0
	v_fma_f32 v47, v93, v37, v37
	v_add_f32_e32 v45, 1.0, v45
	v_div_scale_f32 v93, s[2:3], v36, v36, 2.0
	v_rcp_f32_e32 v99, v49
	v_div_scale_f32 v95, s[6:7], v45, v45, 2.0
	v_rcp_f32_e32 v100, v93
	v_rcp_f32_e32 v101, v95
	v_fma_f32 v103, -v49, v99, 1.0
	v_div_scale_f32 v51, vcc, 2.0, v44, 2.0
	v_fma_f32 v104, -v93, v100, 1.0
	v_fmac_f32_e32 v99, v103, v99
	v_div_scale_f32 v94, s[2:3], 2.0, v36, 2.0
	v_fma_f32 v105, -v95, v101, 1.0
	v_fmac_f32_e32 v100, v104, v100
	v_mul_f32_e32 v103, v51, v99
	v_div_scale_f32 v96, s[6:7], 2.0, v45, 2.0
	v_fmac_f32_e32 v101, v105, v101
	v_mul_f32_e32 v104, v94, v100
	v_fma_f32 v107, -v49, v103, v51
	v_mul_f32_e32 v47, 0x3f4c422a, v47
	v_mul_f32_e32 v105, v96, v101
	v_fma_f32 v108, -v93, v104, v94
	v_fmac_f32_e32 v103, v107, v99
	v_add_f32_e32 v47, v47, v47
	v_fma_f32 v109, -v95, v105, v96
	v_fmac_f32_e32 v104, v108, v100
	v_fma_f32 v49, -v49, v103, v51
	v_mul_f32_e32 v47, 0x3fb8aa3b, v47
	v_fmac_f32_e32 v105, v109, v101
	v_fma_f32 v51, -v93, v104, v94
	v_div_fmas_f32 v49, v49, v99, v103
	s_mov_b64 vcc, s[2:3]
	v_exp_f32_e32 v47, v47
	v_fma_f32 v93, -v95, v105, v96
	v_div_fixup_f32 v44, v49, v44, 2.0
	v_div_fmas_f32 v49, v51, v100, v104
	s_mov_b64 vcc, s[6:7]
	v_sub_f32_e32 v44, 1.0, v44
	v_div_fixup_f32 v36, v49, v36, 2.0
	v_div_fmas_f32 v49, v93, v101, v105
	v_add_f32_e32 v44, 1.0, v44
	v_sub_f32_e32 v36, 1.0, v36
	v_div_fixup_f32 v45, v49, v45, 2.0
	v_mul_f32_e32 v51, v48, v44
	v_add_f32_e32 v36, 1.0, v36
	v_sub_f32_e32 v44, 1.0, v45
	v_lshlrev_b32_e32 v46, 16, v38
	v_add_f32_e32 v47, 1.0, v47
	v_mul_f32_e32 v50, v50, v36
	v_add_f32_e32 v36, 1.0, v44
	v_div_scale_f32 v97, s[8:9], v47, v47, 2.0
	v_mul_f32_e32 v92, v92, v36
	v_mul_f32_e32 v36, 0x3d372713, v46
	v_rcp_f32_e32 v102, v97
	v_mul_f32_e32 v36, v36, v46
	v_fma_f32 v36, v36, v46, v46
	v_mul_f32_e32 v36, 0x3f4c422a, v36
	v_add_f32_e32 v36, v36, v36
	v_fma_f32 v106, -v97, v102, 1.0
	v_mul_f32_e32 v36, 0x3fb8aa3b, v36
	v_div_scale_f32 v98, s[8:9], 2.0, v47, 2.0
	v_fmac_f32_e32 v102, v106, v102
	v_exp_f32_e32 v36, v36
	v_mul_f32_e32 v106, v98, v102
	v_fma_f32 v110, -v97, v106, v98
	v_fmac_f32_e32 v106, v110, v102
	v_fma_f32 v94, -v97, v106, v98
	s_mov_b64 vcc, s[8:9]
	v_add_f32_e32 v36, 1.0, v36
	v_div_fmas_f32 v44, v94, v102, v106
	v_div_scale_f32 v45, s[2:3], v36, v36, 2.0
	v_div_fixup_f32 v44, v44, v47, 2.0
	v_rcp_f32_e32 v47, v45
	v_sub_f32_e32 v44, 1.0, v44
	v_mul_f32_e32 v37, 0.5, v37
	v_add_f32_e32 v44, 1.0, v44
	v_mul_f32_e32 v93, v37, v44
	v_fma_f32 v37, -v45, v47, 1.0
	v_fmac_f32_e32 v47, v37, v47
	v_div_scale_f32 v37, vcc, 2.0, v36, 2.0
	v_mul_f32_e32 v44, v37, v47
	v_fma_f32 v48, -v45, v44, v37
	v_fmac_f32_e32 v44, v48, v47
	v_and_b32_e32 v38, 0xffff0000, v38
	v_fma_f32 v37, -v45, v44, v37
	v_mul_f32_e32 v45, 0x3d372713, v38
	v_mul_f32_e32 v45, v45, v38
	v_fma_f32 v45, v45, v38, v38
	v_mul_f32_e32 v45, 0x3f4c422a, v45
	v_add_f32_e32 v45, v45, v45
	v_mul_f32_e32 v45, 0x3fb8aa3b, v45
	v_exp_f32_e32 v45, v45
	v_div_fmas_f32 v37, v37, v47, v44
	v_div_fixup_f32 v36, v37, v36, 2.0
	v_sub_f32_e32 v36, 1.0, v36
	v_add_f32_e32 v37, 1.0, v45
	v_div_scale_f32 v44, s[2:3], v37, v37, 2.0
	v_rcp_f32_e32 v45, v44
	v_mul_f32_e32 v46, 0.5, v46
	v_add_f32_e32 v36, 1.0, v36
	v_mul_f32_e32 v94, v46, v36
	v_fma_f32 v36, -v44, v45, 1.0
	v_fmac_f32_e32 v45, v36, v45
	v_div_scale_f32 v36, vcc, 2.0, v37, 2.0
	v_mul_f32_e32 v46, v36, v45
	v_fma_f32 v47, -v44, v46, v36
	v_fmac_f32_e32 v46, v47, v45
	v_fma_f32 v36, -v44, v46, v36
	v_lshlrev_b32_e32 v44, 16, v39
	v_mul_f32_e32 v47, 0x3d372713, v44
	v_mul_f32_e32 v47, v47, v44
	v_fma_f32 v47, v47, v44, v44
	v_mul_f32_e32 v47, 0x3f4c422a, v47
	v_add_f32_e32 v47, v47, v47
	v_mul_f32_e32 v47, 0x3fb8aa3b, v47
	v_exp_f32_e32 v47, v47
	v_div_fmas_f32 v36, v36, v45, v46
	v_div_fixup_f32 v36, v36, v37, 2.0
	v_sub_f32_e32 v36, 1.0, v36
	v_add_f32_e32 v37, 1.0, v47
	v_div_scale_f32 v45, s[2:3], v37, v37, 2.0
	v_rcp_f32_e32 v46, v45
	v_mul_f32_e32 v38, 0.5, v38
	v_add_f32_e32 v36, 1.0, v36
	v_mul_f32_e32 v95, v38, v36
; __device__ __forceinline__ float lo_f(unsigned w) { return __uint_as_float(w << 16); }
; __device__ __forceinline__ float hi_f(unsigned w) { return __uint_as_float(w & 0xffff0000u); }
; __device__ void phase_post(const Ctx& c, int l, bool ctx_full) {
;     ...
;                 fv[i * 8 + 0] = gelu_tanh(lo_f(zv.x)); fv[i * 8 + 1] = gelu_tanh(hi_f(zv.x)); fv[i * 8 + 2] = gelu_tanh(lo_f(zv.y)); fv[i * 8 + 3] = gelu_tanh(hi_f(zv.y));
;                 fv[i * 8 + 4] = gelu_tanh(lo_f(zv.z)); fv[i * 8 + 5] = gelu_tanh(hi_f(zv.z)); fv[i * 8 + 6] = gelu_tanh(lo_f(zv.w)); fv[i * 8 + 7] = gelu_tanh(hi_f(zv.w));
; #pragma unroll
;                 for (int j = 0; j < 8; ++j) ss += fv[i * 8 + j] * fv[i * 8 + j]; }
	v_fma_f32 v36, -v45, v46, 1.0
	v_fmac_f32_e32 v46, v36, v46
	v_div_scale_f32 v36, vcc, 2.0, v37, 2.0
	v_mul_f32_e32 v38, v36, v46
	v_fma_f32 v47, -v45, v38, v36
	v_fmac_f32_e32 v38, v47, v46
	v_and_b32_e32 v39, 0xffff0000, v39
	v_fma_f32 v36, -v45, v38, v36
	v_mul_f32_e32 v45, 0x3d372713, v39
	v_mul_f32_e32 v45, v45, v39
	v_fma_f32 v45, v45, v39, v39
	v_mul_f32_e32 v45, 0x3f4c422a, v45
	v_add_f32_e32 v45, v45, v45
	v_mul_f32_e32 v45, 0x3fb8aa3b, v45
	v_exp_f32_e32 v45, v45
	v_div_fmas_f32 v36, v36, v46, v38
	v_div_fixup_f32 v36, v36, v37, 2.0
	v_sub_f32_e32 v36, 1.0, v36
	v_add_f32_e32 v37, 1.0, v45
	v_div_scale_f32 v38, s[2:3], v37, v37, 2.0
	v_rcp_f32_e32 v45, v38
	v_mul_f32_e32 v44, 0.5, v44
	v_add_f32_e32 v36, 1.0, v36
	v_mul_f32_e32 v96, v44, v36
	v_fma_f32 v36, -v38, v45, 1.0
	v_fmac_f32_e32 v45, v36, v45
	v_div_scale_f32 v36, vcc, 2.0, v37, 2.0
	v_mul_f32_e32 v44, v36, v45
	v_fma_f32 v46, -v38, v44, v36
	v_fmac_f32_e32 v44, v46, v45
	v_fma_f32 v36, -v38, v44, v36
	v_div_fmas_f32 v36, v36, v45, v44
	v_div_fixup_f32 v36, v36, v37, 2.0
	v_sub_f32_e32 v36, 1.0, v36
	v_mul_f32_e32 v37, 0.5, v39
	v_add_f32_e32 v36, 1.0, v36
	v_mul_f32_e32 v97, v37, v36
	v_lshlrev_b32_e32 v36, 16, v32
	v_mul_f32_e32 v37, 0x3d372713, v36
	v_mul_f32_e32 v37, v37, v36
	v_fma_f32 v37, v37, v36, v36
	v_mul_f32_e32 v37, 0x3f4c422a, v37
	v_add_f32_e32 v37, v37, v37
	v_mul_f32_e32 v37, 0x3fb8aa3b, v37
	v_exp_f32_e32 v37, v37
	v_and_b32_e32 v32, 0xffff0000, v32
	v_mul_f32_e32 v36, 0.5, v36
	v_mul_f32_e32 v44, v50, v50
	v_add_f32_e32 v37, 1.0, v37
	v_div_scale_f32 v38, s[2:3], v37, v37, 2.0
	v_rcp_f32_e32 v39, v38
	v_fmac_f32_e32 v44, v51, v51
	v_fmac_f32_e32 v44, v92, v92
	v_fmac_f32_e32 v44, v93, v93
	v_fma_f32 v45, -v38, v39, 1.0
	v_fmac_f32_e32 v39, v45, v39
	v_div_scale_f32 v45, vcc, 2.0, v37, 2.0
	v_mul_f32_e32 v46, v45, v39
	v_fma_f32 v47, -v38, v46, v45
	v_fmac_f32_e32 v46, v47, v39
	v_fma_f32 v38, -v38, v46, v45
	v_mul_f32_e32 v45, 0x3d372713, v32
	v_mul_f32_e32 v45, v45, v32
	v_fma_f32 v45, v45, v32, v32
	v_mul_f32_e32 v45, 0x3f4c422a, v45
	v_add_f32_e32 v45, v45, v45
	v_mul_f32_e32 v45, 0x3fb8aa3b, v45
	v_exp_f32_e32 v45, v45
	v_div_fmas_f32 v38, v38, v39, v46
	v_div_fixup_f32 v37, v38, v37, 2.0
	v_sub_f32_e32 v37, 1.0, v37
	v_add_f32_e32 v38, 1.0, v45
	v_div_scale_f32 v39, s[2:3], v38, v38, 2.0
	v_rcp_f32_e32 v45, v39
	v_add_f32_e32 v37, 1.0, v37
	v_mul_f32_e32 v98, v36, v37
	v_mul_f32_e32 v32, 0.5, v32
	v_fma_f32 v36, -v39, v45, 1.0
	v_fmac_f32_e32 v45, v36, v45
	v_div_scale_f32 v36, vcc, 2.0, v38, 2.0
	v_mul_f32_e32 v37, v36, v45
	v_fma_f32 v46, -v39, v37, v36
	v_fmac_f32_e32 v37, v46, v45
	v_fma_f32 v36, -v39, v37, v36
	v_lshlrev_b32_e32 v39, 16, v33
	v_mul_f32_e32 v46, 0x3d372713, v39
	v_mul_f32_e32 v46, v46, v39
	v_fma_f32 v46, v46, v39, v39
	v_mul_f32_e32 v46, 0x3f4c422a, v46
	v_add_f32_e32 v46, v46, v46
	v_mul_f32_e32 v46, 0x3fb8aa3b, v46
	v_exp_f32_e32 v46, v46
	v_div_fmas_f32 v36, v36, v45, v37
	v_div_fixup_f32 v36, v36, v38, 2.0
	v_sub_f32_e32 v36, 1.0, v36
	v_add_f32_e32 v37, 1.0, v46
	v_div_scale_f32 v38, s[2:3], v37, v37, 2.0
	v_rcp_f32_e32 v45, v38
	v_add_f32_e32 v36, 1.0, v36
	v_mul_f32_e32 v99, v32, v36
	v_and_b32_e32 v33, 0xffff0000, v33
	v_fma_f32 v32, -v38, v45, 1.0
	v_fmac_f32_e32 v45, v32, v45
	v_div_scale_f32 v32, vcc, 2.0, v37, 2.0
	v_mul_f32_e32 v36, v32, v45
	v_fma_f32 v46, -v38, v36, v32
	v_fmac_f32_e32 v36, v46, v45
	v_fma_f32 v32, -v38, v36, v32
	v_mul_f32_e32 v38, 0x3d372713, v33
	v_mul_f32_e32 v38, v38, v33
	v_fma_f32 v38, v38, v33, v33
	v_mul_f32_e32 v38, 0x3f4c422a, v38
	v_add_f32_e32 v38, v38, v38
	v_mul_f32_e32 v38, 0x3fb8aa3b, v38
	v_exp_f32_e32 v38, v38
	v_div_fmas_f32 v32, v32, v45, v36
	v_div_fixup_f32 v32, v32, v37, 2.0
	v_sub_f32_e32 v32, 1.0, v32
	v_add_f32_e32 v36, 1.0, v38
	v_div_scale_f32 v37, s[2:3], v36, v36, 2.0
	v_rcp_f32_e32 v38, v37
	v_mul_f32_e32 v39, 0.5, v39
	v_add_f32_e32 v32, 1.0, v32
	v_mul_f32_e32 v100, v39, v32
	v_fma_f32 v32, -v37, v38, 1.0
	v_fmac_f32_e32 v38, v32, v38
	v_div_scale_f32 v32, vcc, 2.0, v36, 2.0
	v_mul_f32_e32 v39, v32, v38
	v_fma_f32 v45, -v37, v39, v32
	v_fmac_f32_e32 v39, v45, v38
	v_fma_f32 v32, -v37, v39, v32
	v_div_fmas_f32 v32, v32, v38, v39
	v_div_fixup_f32 v32, v32, v36, 2.0
	v_mul_f32_e32 v39, 0.5, v33
	v_lshlrev_b32_e32 v33, 16, v34
	v_sub_f32_e32 v38, 1.0, v32
	v_and_b32_e32 v32, 0xffff0000, v34
	v_mul_f32_e32 v34, 0x3d372713, v33
	v_mul_f32_e32 v34, v34, v33
	v_mov_b32_e32 v36, v33
	v_fmac_f32_e32 v36, v34, v36
	v_mul_f32_e32 v34, 0x3f4c422a, v36
	v_add_f32_e32 v34, v34, v34
	v_mul_f32_e32 v34, 0x3fb8aa3b, v34
	v_exp_f32_e32 v37, v34
	v_mul_f32_e32 v34, 0x3d372713, v32
	v_mul_f32_e32 v34, v34, v32
	v_mov_b32_e32 v36, v32
	v_fmac_f32_e32 v36, v34, v36
	v_mul_f32_e32 v34, 0x3f4c422a, v36
	v_add_f32_e32 v34, v34, v34
	v_mul_f32_e32 v34, 0x3fb8aa3b, v34
	v_exp_f32_e32 v36, v34
	v_add_f32_e32 v34, 1.0, v38
	v_mul_f32_e32 v101, v39, v34
	v_fmac_f32_e32 v44, v94, v94
	v_pk_add_f32 v[36:37], v[36:37], 1.0 op_sel_hi:[1,0]
	v_fmac_f32_e32 v44, v95, v95
	v_div_scale_f32 v34, s[2:3], v37, v37, 2.0
	v_rcp_f32_e32 v38, v34
	v_fmac_f32_e32 v44, v96, v96
	v_fmac_f32_e32 v44, v97, v97
	v_fmac_f32_e32 v44, v98, v98
	v_fma_f32 v39, -v34, v38, 1.0
	v_fmac_f32_e32 v38, v39, v38
	v_div_scale_f32 v39, vcc, 2.0, v37, 2.0
	v_mul_f32_e32 v45, v39, v38
	v_fma_f32 v46, -v34, v45, v39
	v_fmac_f32_e32 v45, v46, v38
	v_fma_f32 v34, -v34, v45, v39
	v_div_scale_f32 v39, s[2:3], v36, v36, 2.0
	v_rcp_f32_e32 v46, v39
	v_div_fmas_f32 v34, v34, v38, v45
	v_div_fixup_f32 v37, v34, v37, 2.0
	v_fmac_f32_e32 v44, v99, v99
	v_fma_f32 v34, -v39, v46, 1.0
	v_fmac_f32_e32 v46, v34, v46
	v_div_scale_f32 v34, vcc, 2.0, v36, 2.0
; __device__ __forceinline__ unsigned cvt_pk_bf16(float lo, float hi) { unsigned r; asm volatile("v_cvt_pk_bf16_f32 %0, %1, %2" : "=v"(r) : "v"(lo), "v"(hi)); return r; }
; __device__ __forceinline__ float lo_f(unsigned w) { return __uint_as_float(w << 16); }
; __device__ __forceinline__ float hi_f(unsigned w) { return __uint_as_float(w & 0xffff0000u); }
; __device__ void phase_post(const Ctx& c, int l, bool ctx_full) {
;     ...
;             ss = wave_sum(ss, c.lane); const float rstd = rsqrtf(ss * (1.f / 1024.f) + EPS);
; #pragma unroll
;             for (int i = 0; i < 2; ++i) { const int cc = i * 512 + c.lane * 8;
;                 const f32x4 g0 = *(const f32x4*)(gv + cc), g1 = *(const f32x4*)(gv + cc + 4);
;                 u32x4 w;
;                 w.x = cvt_pk_bf16(fv[i * 8 + 0] * rstd * g0[0], fv[i * 8 + 1] * rstd * g0[1]); w.y = cvt_pk_bf16(fv[i * 8 + 2] * rstd * g0[2], fv[i * 8 + 3] * rstd * g0[3]);
;                 w.z = cvt_pk_bf16(fv[i * 8 + 4] * rstd * g1[0], fv[i * 8 + 5] * rstd * g1[1]); w.w = cvt_pk_bf16(fv[i * 8 + 6] * rstd * g1[2], fv[i * 8 + 7] * rstd * g1[3]);
;                 *(u32x4*)(VN + (size_t)row * 1024 + cc) = w; }
; #pragma unroll
;             for (int i = 0; i < 2; ++i) { const int cc = i * 512 + c.lane * 8;
;                 float a[8] = {0.f, 0.f, 0.f, 0.f, 0.f, 0.f, 0.f, 0.f};
; #pragma unroll
;                 for (int k = 0; k < 3; ++k) { const int tt = t + k - 1;
;                     if (tt >= 0 && tt < slen) { const bf16_t* z2 = zr + (ptrdiff_t)(k - 1) * IN_DIM;
;                         const u32x4 cg = *(const u32x4*)(z2 + OFF_CC + cc), hh = *(const u32x4*)(z2 + OFF_CH + cc);
;                         const f32x4 w0 = *(const f32x4*)(wsc + k * 1024 + cc), w1 = *(const f32x4*)(wsc + k * 1024 + cc + 4);
;                         a[0] += w0[0] * lo_f(cg.x) * lo_f(hh.x); a[1] += w0[1] * hi_f(cg.x) * hi_f(hh.x); a[2] += w0[2] * lo_f(cg.y) * lo_f(hh.y); a[3] += w0[3] * hi_f(cg.y) * hi_f(hh.y);
	v_mul_f32_e32 v38, v34, v46
	v_fma_f32 v45, -v39, v38, v34
	v_fmac_f32_e32 v38, v45, v46
	v_fma_f32 v34, -v39, v38, v34
	v_div_fmas_f32 v34, v34, v46, v38
	v_lshlrev_b32_e32 v39, 16, v35
	v_div_fixup_f32 v36, v34, v36, 2.0
	v_mul_f32_e32 v34, 0x3d372713, v39
	v_and_b32_e32 v38, 0xffff0000, v35
	v_mul_f32_e32 v34, v34, v39
	v_mov_b32_e32 v35, v39
	v_fmac_f32_e32 v35, v34, v35
	v_mul_f32_e32 v34, 0x3f4c422a, v35
	v_add_f32_e32 v34, v34, v34
	v_mul_f32_e32 v34, 0x3fb8aa3b, v34
	v_exp_f32_e32 v35, v34
	v_mul_f32_e32 v34, 0x3d372713, v38
	v_mul_f32_e32 v34, v34, v38
	v_mov_b32_e32 v45, v38
	v_fmac_f32_e32 v45, v34, v45
	v_mul_f32_e32 v34, 0x3f4c422a, v45
	v_add_f32_e32 v34, v34, v34
	v_mul_f32_e32 v34, 0x3fb8aa3b, v34
	v_exp_f32_e32 v34, v34
	v_pk_add_f32 v[36:37], v[36:37], 1.0 op_sel_hi:[1,0] neg_lo:[1,0] neg_hi:[1,0]
	v_pk_mul_f32 v[32:33], v[32:33], 0.5 op_sel_hi:[1,0]
	v_pk_add_f32 v[36:37], v[36:37], 1.0 op_sel_hi:[1,0]
	v_fmac_f32_e32 v44, v100, v100
	v_pk_mul_f32 v[48:49], v[32:33], v[36:37]
	v_fmac_f32_e32 v44, v101, v101
	v_pk_add_f32 v[32:33], v[34:35], 1.0 op_sel_hi:[1,0]
	v_pk_mul_f32 v[34:35], v[48:49], v[48:49]
	v_div_scale_f32 v102, s[2:3], v33, v33, 2.0
	v_add_f32_e32 v35, v35, v44
	v_add_f32_e32 v104, v34, v35
	ds_read_b128 v[34:37], v245 offset:12304
	ds_read_b128 v[44:47], v245 offset:12288
	v_rcp_f32_e32 v103, v102
	v_pk_mul_f32 v[38:39], v[38:39], 0.5 op_sel_hi:[1,0]
	v_cmp_ne_u32_e64 s[6:7], 0, v127
	v_fma_f32 v105, -v102, v103, 1.0
	v_fmac_f32_e32 v103, v105, v103
	v_div_scale_f32 v105, vcc, 2.0, v33, 2.0
	v_mul_f32_e32 v106, v105, v103
	v_fma_f32 v107, -v102, v106, v105
	v_fmac_f32_e32 v106, v107, v103
	v_fma_f32 v102, -v102, v106, v105
	v_div_scale_f32 v105, s[2:3], v32, v32, 2.0
	v_rcp_f32_e32 v107, v105
	v_div_fmas_f32 v102, v102, v103, v106
	v_div_fixup_f32 v33, v102, v33, 2.0
	v_fma_f32 v102, -v105, v107, 1.0
	v_fmac_f32_e32 v107, v102, v107
	v_div_scale_f32 v102, vcc, 2.0, v32, 2.0
	v_mul_f32_e32 v103, v102, v107
	v_fma_f32 v106, -v105, v103, v102
	v_fmac_f32_e32 v103, v106, v107
	v_fma_f32 v102, -v105, v103, v102
	v_div_fmas_f32 v102, v102, v107, v103
	v_div_fixup_f32 v32, v102, v32, 2.0
	v_pk_add_f32 v[32:33], v[32:33], 1.0 op_sel_hi:[1,0] neg_lo:[1,0] neg_hi:[1,0]
	s_nop 0
	v_pk_add_f32 v[32:33], v[32:33], 1.0 op_sel_hi:[1,0]
	s_nop 0
	v_pk_mul_f32 v[38:39], v[38:39], v[32:33]
	s_nop 0
	v_pk_mul_f32 v[32:33], v[38:39], v[38:39]
	s_nop 0
	v_add_f32_e32 v33, v33, v104
	v_add_f32_e32 v32, v32, v33
	ds_bpermute_b32 v33, v120, v32
	s_waitcnt lgkmcnt(0)
	v_add_f32_e32 v32, v32, v33
	ds_bpermute_b32 v33, v121, v32
	s_waitcnt lgkmcnt(0)
	v_add_f32_e32 v32, v32, v33
	ds_bpermute_b32 v33, v55, v32
	s_waitcnt lgkmcnt(0)
	v_add_f32_e32 v32, v32, v33
	ds_bpermute_b32 v33, v67, v32
	s_waitcnt lgkmcnt(0)
	v_add_f32_e32 v32, v32, v33
	ds_bpermute_b32 v33, v118, v32
	s_waitcnt lgkmcnt(0)
	v_add_f32_e32 v32, v32, v33
	ds_bpermute_b32 v33, v119, v32
	s_waitcnt lgkmcnt(0)
	v_add_f32_e32 v32, v32, v33
	v_fmamk_f32 v32, v32, 0x3a800000, v124
	v_mul_f32_e32 v33, 0x4b800000, v32
	v_cmp_gt_f32_e32 vcc, s78, v32
	s_nop 1
	v_cndmask_b32_e32 v32, v32, v33, vcc
	v_rsq_f32_e32 v32, v32
	s_nop 0
	v_mul_f32_e32 v33, 0x45800000, v32
	v_cndmask_b32_e32 v102, v32, v33, vcc
	v_mul_f32_e32 v51, v51, v102
	v_mul_f32_e32 v50, v50, v102
	s_waitcnt lgkmcnt(0)
	v_mul_f32_e32 v44, v44, v51
	v_mul_f32_e32 v45, v45, v50
	v_cvt_pk_bf16_f32 v44, v44, v45
	v_mul_f32_e32 v45, v92, v102
	v_mul_f32_e32 v45, v46, v45
	v_mul_f32_e32 v46, v93, v102
	v_mul_f32_e32 v46, v47, v46
	v_cvt_pk_bf16_f32 v45, v45, v46
	v_mul_f32_e32 v46, v94, v102
	v_mul_f32_e32 v34, v34, v46
	v_mul_f32_e32 v46, v95, v102
	v_lshlrev_b64 v[32:33], 11, v[52:53]
	v_mul_f32_e32 v35, v35, v46
	v_cvt_pk_bf16_f32 v46, v34, v35
	v_mul_f32_e32 v34, v96, v102
	v_mul_f32_e32 v35, v97, v102
	v_lshl_add_u64 v[50:51], v[84:85], 0, v[32:33]
	v_mul_f32_e32 v34, v36, v34
	v_mul_f32_e32 v35, v37, v35
	v_cvt_pk_bf16_f32 v47, v34, v35
	global_store_dwordx4 v[50:51], v[44:47], off
	ds_read_b128 v[34:37], v245 offset:14336
	s_nop 0
	ds_read_b128 v[44:47], v245 offset:14352
	v_mul_f32_e32 v53, v98, v102
	v_mul_f32_e32 v38, v38, v102
	s_waitcnt lgkmcnt(1)
	v_mul_f32_e32 v34, v34, v53
	v_mul_f32_e32 v53, v99, v102
	v_mul_f32_e32 v35, v35, v53
	v_cvt_pk_bf16_f32 v34, v34, v35
	v_mul_f32_e32 v35, v100, v102
	v_mul_f32_e32 v35, v36, v35
	v_mul_f32_e32 v36, v101, v102
	v_mul_f32_e32 v36, v37, v36
	v_cvt_pk_bf16_f32 v35, v35, v36
	v_mul_f32_e32 v36, v49, v102
	v_mul_f32_e32 v37, v48, v102
	s_waitcnt lgkmcnt(0)
	v_mul_f32_e32 v36, v44, v36
	v_mul_f32_e32 v37, v45, v37
	v_cvt_pk_bf16_f32 v36, v36, v37
	v_mul_f32_e32 v37, v39, v102
	v_mul_f32_e32 v37, v46, v37
	v_mul_f32_e32 v38, v47, v38
	v_cvt_pk_bf16_f32 v37, v37, v38
	v_mov_b32_e32 v38, 0
	global_store_dwordx4 v[50:51], v[34:37], off offset:1024
	v_mov_b32_e32 v39, v38
	v_mov_b32_e32 v44, v38
	v_mov_b32_e32 v45, v38
	v_mov_b32_e32 v46, v38
	v_mov_b32_e32 v47, v38
	v_mov_b32_e32 v50, v38
	v_mov_b32_e32 v51, v38
	s_and_saveexec_b64 s[2:3], s[6:7]
	s_cbranch_execz .LBB0_1464
	v_add_co_u32_e32 v34, vcc, 0xffffc000, v42
	s_nop 1
	v_addc_co_u32_e32 v35, vcc, -1, v43, vcc
	v_mov_b64_e32 v[34:35], v[184:185]
	v_mov_b64_e32 v[36:37], v[186:187]
	v_add_co_u32_e32 v38, vcc, 0xffffd000, v42
	v_lshlrev_b32_e32 v50, 16, v36
	v_addc_co_u32_e32 v39, vcc, -1, v43, vcc
	ds_read_b128 v[42:45], v245 offset:0
	v_mov_b64_e32 v[46:47], v[188:189]
	v_mov_b64_e32 v[48:49], v[190:191]
	ds_read_b128 v[92:95], v245 offset:16
	v_lshlrev_b32_e32 v38, 16, v34
	v_and_b32_e32 v39, 0xffff0000, v34
	v_lshlrev_b32_e32 v34, 16, v35
	v_and_b32_e32 v35, 0xffff0000, v35
	v_and_b32_e32 v51, 0xffff0000, v36
	v_lshlrev_b32_e32 v36, 16, v37
	v_and_b32_e32 v37, 0xffff0000, v37
	s_waitcnt lgkmcnt(1)
	v_pk_mul_f32 v[38:39], v[42:43], v[38:39]
	s_waitcnt lgkmcnt(1)
	v_lshlrev_b32_e32 v42, 16, v46
	v_and_b32_e32 v43, 0xffff0000, v46
	v_pk_mul_f32 v[34:35], v[44:45], v[34:35]
	v_lshlrev_b32_e32 v44, 16, v47
	v_and_b32_e32 v45, 0xffff0000, v47
	s_waitcnt lgkmcnt(0)
	v_pk_mul_f32 v[46:47], v[92:93], v[50:51]
	v_lshlrev_b32_e32 v50, 16, v48
	v_and_b32_e32 v51, 0xffff0000, v48
	v_pk_mul_f32 v[36:37], v[94:95], v[36:37]
	v_lshlrev_b32_e32 v48, 16, v49
	v_and_b32_e32 v49, 0xffff0000, v49
	v_pk_fma_f32 v[38:39], v[38:39], v[42:43], 0 op_sel_hi:[1,1,0]
	v_pk_fma_f32 v[44:45], v[34:35], v[44:45], 0 op_sel_hi:[1,1,0]
	v_pk_fma_f32 v[46:47], v[46:47], v[50:51], 0 op_sel_hi:[1,1,0]
	v_pk_fma_f32 v[50:51], v[36:37], v[48:49], 0 op_sel_hi:[1,1,0]
; __device__ __forceinline__ float lo_f(unsigned w) { return __uint_as_float(w << 16); }
; __device__ __forceinline__ float hi_f(unsigned w) { return __uint_as_float(w & 0xffff0000u); }
; __device__ void phase_post(const Ctx& c, int l, bool ctx_full) {
;     ...
;             for (int i = 0; i < 2; ++i) { const int cc = i * 512 + c.lane * 8;
;                 float a[8] = {0.f, 0.f, 0.f, 0.f, 0.f, 0.f, 0.f, 0.f};
; #pragma unroll
;                 for (int k = 0; k < 3; ++k) { const int tt = t + k - 1;
;                     if (tt >= 0 && tt < slen) { const bf16_t* z2 = zr + (ptrdiff_t)(k - 1) * IN_DIM;
;                         const u32x4 cg = *(const u32x4*)(z2 + OFF_CC + cc), hh = *(const u32x4*)(z2 + OFF_CH + cc);
;                         const f32x4 w0 = *(const f32x4*)(wsc + k * 1024 + cc), w1 = *(const f32x4*)(wsc + k * 1024 + cc + 4);
;                         a[0] += w0[0] * lo_f(cg.x) * lo_f(hh.x); a[1] += w0[1] * hi_f(cg.x) * hi_f(hh.x); a[2] += w0[2] * lo_f(cg.y) * lo_f(hh.y); a[3] += w0[3] * hi_f(cg.y) * hi_f(hh.y);
;                         a[4] += w1[0] * lo_f(cg.z) * lo_f(hh.z); a[5] += w1[1] * hi_f(cg.z) * hi_f(hh.z); a[6] += w1[2] * lo_f(cg.w) * lo_f(hh.w); a[7] += w1[3] * hi_f(cg.w) * hi_f(hh.w); } }
.LBB0_1464:
	s_or_b64 exec, exec, s[2:3]
	v_lshl_add_u64 v[34:35], v[40:41], 0, s[18:19]
	v_lshl_add_u64 v[36:37], v[34:35], 0, v[56:57]
	v_mov_b64_e32 v[92:93], v[192:193]
	v_mov_b64_e32 v[94:95], v[194:195]
	v_lshl_add_u64 v[36:37], v[40:41], 0, s[68:69]
	v_lshl_add_u64 v[42:43], v[36:37], 0, v[56:57]
	v_mov_b64_e32 v[96:97], v[196:197]
	v_mov_b64_e32 v[98:99], v[198:199]
	ds_read_b128 v[100:103], v245 offset:4096
	ds_read_b128 v[104:107], v245 offset:4112
	v_cmp_ne_u32_e64 s[8:9], s76, v127
	s_waitcnt lgkmcnt(3)
	v_lshlrev_b32_e32 v42, 16, v92
	v_and_b32_e32 v43, 0xffff0000, v92
	v_lshlrev_b32_e32 v92, 16, v93
	v_and_b32_e32 v93, 0xffff0000, v93
	v_lshlrev_b32_e32 v108, 16, v94
	v_and_b32_e32 v109, 0xffff0000, v94
	v_lshlrev_b32_e32 v94, 16, v95
	v_and_b32_e32 v95, 0xffff0000, v95
	s_waitcnt lgkmcnt(2)
	v_lshlrev_b32_e32 v48, 16, v96
	v_and_b32_e32 v49, 0xffff0000, v96
	v_lshlrev_b32_e32 v96, 16, v97
	v_and_b32_e32 v97, 0xffff0000, v97
	v_lshlrev_b32_e32 v110, 16, v98
	v_and_b32_e32 v111, 0xffff0000, v98
	v_lshlrev_b32_e32 v98, 16, v99
	v_and_b32_e32 v99, 0xffff0000, v99
	s_waitcnt lgkmcnt(1)
	v_pk_mul_f32 v[42:43], v[100:101], v[42:43]
	v_pk_mul_f32 v[92:93], v[102:103], v[92:93]
	s_waitcnt lgkmcnt(0)
	v_pk_mul_f32 v[100:101], v[104:105], v[108:109]
	v_pk_mul_f32 v[94:95], v[106:107], v[94:95]
	v_pk_fma_f32 v[48:49], v[42:43], v[48:49], v[38:39]
	v_pk_fma_f32 v[44:45], v[92:93], v[96:97], v[44:45]
	v_pk_fma_f32 v[42:43], v[100:101], v[110:111], v[46:47]
	v_pk_fma_f32 v[46:47], v[94:95], v[98:99], v[50:51]
	s_and_saveexec_b64 s[2:3], s[8:9]
	s_cbranch_execz .LBB0_1466
	v_lshl_add_u64 v[38:39], v[40:41], 0, v[56:57]
	v_add_co_u32_e32 v38, vcc, 0xa000, v38
	s_nop 1
	v_addc_co_u32_e32 v39, vcc, 0, v39, vcc
	v_mov_b64_e32 v[92:93], v[200:201]
	v_mov_b64_e32 v[94:95], v[202:203]
	v_mov_b64_e32 v[96:97], v[204:205]
	v_mov_b64_e32 v[98:99], v[206:207]
	ds_read_b128 v[100:103], v245 offset:8192
	ds_read_b128 v[104:107], v245 offset:8208
	s_waitcnt lgkmcnt(3)
	v_lshlrev_b32_e32 v38, 16, v92
	v_and_b32_e32 v39, 0xffff0000, v92
	v_lshlrev_b32_e32 v92, 16, v93
	v_and_b32_e32 v93, 0xffff0000, v93
	v_lshlrev_b32_e32 v108, 16, v94
	v_and_b32_e32 v109, 0xffff0000, v94
	v_lshlrev_b32_e32 v94, 16, v95
	v_and_b32_e32 v95, 0xffff0000, v95
	s_waitcnt lgkmcnt(2)
	v_lshlrev_b32_e32 v50, 16, v96
	v_and_b32_e32 v51, 0xffff0000, v96
	v_lshlrev_b32_e32 v96, 16, v97
	v_and_b32_e32 v97, 0xffff0000, v97
	v_lshlrev_b32_e32 v110, 16, v98
	v_and_b32_e32 v111, 0xffff0000, v98
	v_lshlrev_b32_e32 v98, 16, v99
	v_and_b32_e32 v99, 0xffff0000, v99
	s_waitcnt lgkmcnt(1)
	v_pk_mul_f32 v[38:39], v[100:101], v[38:39]
	v_pk_mul_f32 v[92:93], v[102:103], v[92:93]
	s_waitcnt lgkmcnt(0)
	v_pk_mul_f32 v[100:101], v[104:105], v[108:109]
	v_pk_mul_f32 v[94:95], v[106:107], v[94:95]
	v_pk_fma_f32 v[48:49], v[38:39], v[50:51], v[48:49]
	v_pk_fma_f32 v[44:45], v[92:93], v[96:97], v[44:45]
	v_pk_fma_f32 v[42:43], v[100:101], v[110:111], v[42:43]
	v_pk_fma_f32 v[46:47], v[94:95], v[98:99], v[46:47]
; __device__ __forceinline__ unsigned cvt_pk_bf16(float lo, float hi) { unsigned r; asm volatile("v_cvt_pk_bf16_f32 %0, %1, %2" : "=v"(r) : "v"(lo), "v"(hi)); return r; }
; __device__ __forceinline__ float lo_f(unsigned w) { return __uint_as_float(w << 16); }
; __device__ __forceinline__ float hi_f(unsigned w) { return __uint_as_float(w & 0xffff0000u); }
; __device__ void phase_post(const Ctx& c, int l, bool ctx_full) {
;     ...
;             for (int i = 0; i < 2; ++i) { const int cc = i * 512 + c.lane * 8;
;                 float a[8] = {0.f, 0.f, 0.f, 0.f, 0.f, 0.f, 0.f, 0.f};
; #pragma unroll
;                 for (int k = 0; k < 3; ++k) { const int tt = t + k - 1;
;                     if (tt >= 0 && tt < slen) { const bf16_t* z2 = zr + (ptrdiff_t)(k - 1) * IN_DIM;
;                         const u32x4 cg = *(const u32x4*)(z2 + OFF_CC + cc), hh = *(const u32x4*)(z2 + OFF_CH + cc);
;                         const f32x4 w0 = *(const f32x4*)(wsc + k * 1024 + cc), w1 = *(const f32x4*)(wsc + k * 1024 + cc + 4);
;                         a[0] += w0[0] * lo_f(cg.x) * lo_f(hh.x); a[1] += w0[1] * hi_f(cg.x) * hi_f(hh.x); a[2] += w0[2] * lo_f(cg.y) * lo_f(hh.y); a[3] += w0[3] * hi_f(cg.y) * hi_f(hh.y);
;                         a[4] += w1[0] * lo_f(cg.z) * lo_f(hh.z); a[5] += w1[1] * hi_f(cg.z) * hi_f(hh.z); a[6] += w1[2] * lo_f(cg.w) * lo_f(hh.w); a[7] += w1[3] * hi_f(cg.w) * hi_f(hh.w); } }
;                 const u32x4 bg = *(const u32x4*)(zr + OFF_CB + cc);
;                 u32x4 w;
;                 w.x = cvt_pk_bf16(a[0] * lo_f(bg.x), a[1] * hi_f(bg.x)); w.y = cvt_pk_bf16(a[2] * lo_f(bg.y), a[3] * hi_f(bg.y));
;                 w.z = cvt_pk_bf16(a[4] * lo_f(bg.z), a[5] * hi_f(bg.z)); w.w = cvt_pk_bf16(a[6] * lo_f(bg.w), a[7] * hi_f(bg.w));
;                 *(u32x4*)(AM1 + (size_t)row * 1024 + cc) = w; }
.LBB0_1466:
	s_or_b64 exec, exec, s[2:3]
	v_lshl_add_u64 v[38:39], v[40:41], 0, s[70:71]
	v_lshl_add_u64 v[50:51], v[38:39], 0, v[56:57]
	v_mov_b64_e32 v[98:99], v[176:177]
	v_mov_b64_e32 v[100:101], v[178:179]
	v_lshl_add_u64 v[32:33], v[86:87], 0, v[32:33]
	v_mov_b32_e32 v50, 0
	v_mov_b32_e32 v51, 0
	v_mov_b32_e32 v92, 0
	v_mov_b32_e32 v93, 0
	v_mov_b32_e32 v94, 0
	v_mov_b32_e32 v95, 0
	v_mov_b32_e32 v96, 0
	v_lshlrev_b32_e32 v56, 1, v66
	s_waitcnt lgkmcnt(0)
	v_lshlrev_b32_e32 v53, 16, v98
	v_and_b32_e32 v97, 0xffff0000, v98
	v_lshlrev_b32_e32 v98, 16, v99
	v_lshlrev_b32_e32 v102, 16, v100
	v_and_b32_e32 v100, 0xffff0000, v100
	v_and_b32_e32 v99, 0xffff0000, v99
	v_mul_f32_e32 v49, v49, v97
	v_mul_f32_e32 v44, v44, v98
	v_mul_f32_e32 v97, v43, v100
	v_lshlrev_b32_e32 v103, 16, v101
	v_and_b32_e32 v101, 0xffff0000, v101
	v_mul_f32_e32 v48, v48, v53
	v_mul_f32_e32 v45, v45, v99
	v_mul_f32_e32 v53, v42, v102
	v_cvt_pk_bf16_f32 v42, v48, v49
	v_cvt_pk_bf16_f32 v43, v44, v45
	v_cvt_pk_bf16_f32 v44, v53, v97
	v_mov_b32_e32 v97, 0
	v_mul_f32_e32 v46, v46, v103
	v_mul_f32_e32 v47, v47, v101
	v_cvt_pk_bf16_f32 v45, v46, v47
	global_store_dwordx4 v[32:33], v[42:45], off
	s_and_saveexec_b64 s[2:3], s[6:7]
	s_cbranch_execz .LBB0_1468
	v_lshl_add_u64 v[46:47], v[40:41], 0, v[56:57]
	v_add_co_u32_e32 v42, vcc, 0xffffc000, v46
	s_nop 1
	v_addc_co_u32_e32 v43, vcc, -1, v47, vcc
	v_mov_b64_e32 v[42:43], v[208:209]
	v_mov_b64_e32 v[44:45], v[210:211]
	v_add_co_u32_e32 v50, vcc, 0xffffd000, v46
	v_lshlrev_b32_e32 v100, 16, v44
	v_addc_co_u32_e32 v51, vcc, -1, v47, vcc
	ds_read_b128 v[46:49], v245 offset:2048
	v_mov_b64_e32 v[92:93], v[212:213]
	v_mov_b64_e32 v[94:95], v[214:215]
	ds_read_b128 v[96:99], v245 offset:2064
	v_lshlrev_b32_e32 v50, 16, v42
	v_and_b32_e32 v51, 0xffff0000, v42
	v_lshlrev_b32_e32 v42, 16, v43
	v_and_b32_e32 v43, 0xffff0000, v43
	v_and_b32_e32 v101, 0xffff0000, v44
	v_lshlrev_b32_e32 v44, 16, v45
	v_and_b32_e32 v45, 0xffff0000, v45
	s_waitcnt lgkmcnt(1)
	v_pk_mul_f32 v[46:47], v[46:47], v[50:51]
	s_waitcnt lgkmcnt(1)
	v_lshlrev_b32_e32 v50, 16, v92
	v_and_b32_e32 v51, 0xffff0000, v92
	v_pk_mul_f32 v[42:43], v[48:49], v[42:43]
	v_lshlrev_b32_e32 v48, 16, v93
	v_and_b32_e32 v49, 0xffff0000, v93
	s_waitcnt lgkmcnt(0)
	v_pk_mul_f32 v[96:97], v[96:97], v[100:101]
	v_lshlrev_b32_e32 v100, 16, v94
	v_and_b32_e32 v101, 0xffff0000, v94
	v_pk_mul_f32 v[44:45], v[98:99], v[44:45]
	v_lshlrev_b32_e32 v98, 16, v95
	v_and_b32_e32 v99, 0xffff0000, v95
	v_pk_fma_f32 v[50:51], v[46:47], v[50:51], 0 op_sel_hi:[1,1,0]
	v_pk_fma_f32 v[92:93], v[42:43], v[48:49], 0 op_sel_hi:[1,1,0]
	v_pk_fma_f32 v[94:95], v[96:97], v[100:101], 0 op_sel_hi:[1,1,0]
	v_pk_fma_f32 v[96:97], v[44:45], v[98:99], 0 op_sel_hi:[1,1,0]
.LBB0_1468:
	s_or_b64 exec, exec, s[2:3]
	v_lshl_add_u64 v[34:35], v[34:35], 0, v[56:57]
	v_mov_b64_e32 v[42:43], v[218:219]
	v_mov_b64_e32 v[44:45], v[220:221]
	v_lshl_add_u64 v[34:35], v[36:37], 0, v[56:57]
	v_mov_b64_e32 v[34:35], v[222:223]
	v_mov_b64_e32 v[36:37], v[224:225]
	s_nop 0
	ds_read_b128 v[46:49], v245 offset:6144
	ds_read_b128 v[98:101], v245 offset:6160
	s_waitcnt lgkmcnt(2)
	v_lshlrev_b32_e32 v104, 16, v34
	v_lshlrev_b32_e32 v102, 16, v42
	v_and_b32_e32 v103, 0xffff0000, v42
	v_lshlrev_b32_e32 v42, 16, v43
	v_and_b32_e32 v43, 0xffff0000, v43
	v_lshlrev_b32_e32 v106, 16, v44
	v_and_b32_e32 v107, 0xffff0000, v44
	v_lshlrev_b32_e32 v44, 16, v45
	v_and_b32_e32 v45, 0xffff0000, v45
	v_and_b32_e32 v105, 0xffff0000, v34
	v_lshlrev_b32_e32 v34, 16, v35
	v_and_b32_e32 v35, 0xffff0000, v35
	v_lshlrev_b32_e32 v108, 16, v36
	v_and_b32_e32 v109, 0xffff0000, v36
	v_lshlrev_b32_e32 v110, 16, v37
	v_and_b32_e32 v111, 0xffff0000, v37
	s_waitcnt lgkmcnt(1)
	v_pk_mul_f32 v[36:37], v[46:47], v[102:103]
	v_pk_mul_f32 v[42:43], v[48:49], v[42:43]
	s_waitcnt lgkmcnt(0)
	v_pk_mul_f32 v[46:47], v[98:99], v[106:107]
	v_pk_mul_f32 v[48:49], v[100:101], v[44:45]
	v_pk_fma_f32 v[44:45], v[36:37], v[104:105], v[50:51]
	v_pk_fma_f32 v[36:37], v[42:43], v[34:35], v[92:93]
	v_pk_fma_f32 v[34:35], v[46:47], v[108:109], v[94:95]
	v_pk_fma_f32 v[42:43], v[48:49], v[110:111], v[96:97]
	s_and_saveexec_b64 s[2:3], s[8:9]
	s_cbranch_execz .LBB0_1445
	v_lshl_add_u64 v[40:41], v[40:41], 0, v[56:57]
	v_add_co_u32_e32 v40, vcc, 0xa000, v40
	s_nop 1
	v_addc_co_u32_e32 v41, vcc, 0, v41, vcc
	v_mov_b64_e32 v[46:47], v[226:227]
	v_mov_b64_e32 v[48:49], v[228:229]
	v_mov_b64_e32 v[92:93], v[230:231]
	v_mov_b64_e32 v[94:95], v[232:233]
	ds_read_b128 v[96:99], v245 offset:10240
	ds_read_b128 v[100:103], v245 offset:10256
	s_waitcnt lgkmcnt(3)
	v_lshlrev_b32_e32 v40, 16, v46
	v_and_b32_e32 v41, 0xffff0000, v46
	v_lshlrev_b32_e32 v46, 16, v47
	v_and_b32_e32 v47, 0xffff0000, v47
	v_lshlrev_b32_e32 v104, 16, v48
	v_and_b32_e32 v105, 0xffff0000, v48
	v_lshlrev_b32_e32 v48, 16, v49
	v_and_b32_e32 v49, 0xffff0000, v49
	s_waitcnt lgkmcnt(2)
	v_lshlrev_b32_e32 v50, 16, v92
	v_and_b32_e32 v51, 0xffff0000, v92
	v_lshlrev_b32_e32 v92, 16, v93
	v_and_b32_e32 v93, 0xffff0000, v93
	v_lshlrev_b32_e32 v106, 16, v94
	v_and_b32_e32 v107, 0xffff0000, v94
	v_lshlrev_b32_e32 v94, 16, v95
	v_and_b32_e32 v95, 0xffff0000, v95
	s_waitcnt lgkmcnt(1)
	v_pk_mul_f32 v[40:41], v[96:97], v[40:41]
	v_pk_mul_f32 v[46:47], v[98:99], v[46:47]
	s_waitcnt lgkmcnt(0)
	v_pk_mul_f32 v[96:97], v[100:101], v[104:105]
	v_pk_mul_f32 v[48:49], v[102:103], v[48:49]
	v_pk_fma_f32 v[44:45], v[40:41], v[50:51], v[44:45]
	v_pk_fma_f32 v[36:37], v[46:47], v[92:93], v[36:37]
	v_pk_fma_f32 v[34:35], v[96:97], v[106:107], v[34:35]
	v_pk_fma_f32 v[42:43], v[48:49], v[94:95], v[42:43]
	s_branch .LBB0_1445
